# v52 + conv-FFN epilogues: row_shr DPP movs fused into v_add_f32_dpp (384 fewer VALU per tile pair, replaces 192 v_pk_add_f32)
# speedup vs baseline: 1.0134x; 1.0102x over previous
.LBB0_1163:
	s_or_b64 exec, exec, s[12:13]
	v_pk_mul_f32 v[110:111], v[110:111], v[202:203] op_sel_hi:[1,0]
	v_pk_mul_f32 v[108:109], v[108:109], v[202:203] op_sel_hi:[1,0]
	v_pk_mul_f32 v[98:99], v[98:99], v[202:203] op_sel_hi:[1,0]
	v_pk_mul_f32 v[96:97], v[96:97], v[202:203] op_sel_hi:[1,0]
	v_add_u32_e32 v197, s18, v225
	s_waitcnt lgkmcnt(0)
	v_mov_b32_dpp v164, v148 row_shl:15 row_mask:0xf bank_mask:0xf bound_ctrl:1
	v_mov_b32_dpp v148, v148 row_shl:14 row_mask:0xf bank_mask:0xf bound_ctrl:1
	v_mov_b32_dpp v206, v132 row_shl:15 row_mask:0xf bank_mask:0xf bound_ctrl:1
	v_mov_b32_dpp v172, v132 row_shl:14 row_mask:0xf bank_mask:0xf bound_ctrl:1
	v_mov_b32_dpp v165, v149 row_shl:15 row_mask:0xf bank_mask:0xf bound_ctrl:1
	v_mov_b32_dpp v149, v149 row_shl:14 row_mask:0xf bank_mask:0xf bound_ctrl:1
	v_mov_b32_dpp v207, v133 row_shl:15 row_mask:0xf bank_mask:0xf bound_ctrl:1
	v_mov_b32_dpp v173, v133 row_shl:14 row_mask:0xf bank_mask:0xf bound_ctrl:1
	v_mov_b32_dpp v168, v150 row_shl:15 row_mask:0xf bank_mask:0xf bound_ctrl:1
	v_mov_b32_dpp v150, v150 row_shl:14 row_mask:0xf bank_mask:0xf bound_ctrl:1
	v_mov_b32_dpp v212, v134 row_shl:15 row_mask:0xf bank_mask:0xf bound_ctrl:1
	v_mov_b32_dpp v134, v134 row_shl:14 row_mask:0xf bank_mask:0xf bound_ctrl:1
	v_mov_b32_dpp v169, v151 row_shl:15 row_mask:0xf bank_mask:0xf bound_ctrl:1
	v_mov_b32_dpp v151, v151 row_shl:14 row_mask:0xf bank_mask:0xf bound_ctrl:1
	v_mov_b32_dpp v213, v135 row_shl:15 row_mask:0xf bank_mask:0xf bound_ctrl:1
	v_mov_b32_dpp v135, v135 row_shl:14 row_mask:0xf bank_mask:0xf bound_ctrl:1
	v_add_f32_dpp v162, v108, v164 row_shr:1 row_mask:0xf bank_mask:0xf bound_ctrl:1
	v_add_f32_dpp v148, v108, v148 row_shr:2 row_mask:0xf bank_mask:0xf bound_ctrl:1
	v_add_f32_dpp v174, v96, v206 row_shr:1 row_mask:0xf bank_mask:0xf bound_ctrl:1
	v_add_f32_dpp v170, v96, v172 row_shr:2 row_mask:0xf bank_mask:0xf bound_ctrl:1
	v_add_f32_dpp v163, v109, v165 row_shr:1 row_mask:0xf bank_mask:0xf bound_ctrl:1
	v_add_f32_dpp v149, v109, v149 row_shr:2 row_mask:0xf bank_mask:0xf bound_ctrl:1
	v_add_f32_dpp v175, v97, v207 row_shr:1 row_mask:0xf bank_mask:0xf bound_ctrl:1
	v_add_f32_dpp v171, v97, v173 row_shr:2 row_mask:0xf bank_mask:0xf bound_ctrl:1
	v_add_f32_dpp v166, v110, v168 row_shr:1 row_mask:0xf bank_mask:0xf bound_ctrl:1
	v_add_f32_dpp v132, v110, v150 row_shr:2 row_mask:0xf bank_mask:0xf bound_ctrl:1
	v_add_f32_dpp v210, v98, v212 row_shr:1 row_mask:0xf bank_mask:0xf bound_ctrl:1
	v_add_f32_dpp v134, v98, v134 row_shr:2 row_mask:0xf bank_mask:0xf bound_ctrl:1
	v_add_f32_dpp v167, v111, v169 row_shr:1 row_mask:0xf bank_mask:0xf bound_ctrl:1
	v_add_f32_dpp v133, v111, v151 row_shr:2 row_mask:0xf bank_mask:0xf bound_ctrl:1
	v_add_f32_dpp v211, v99, v213 row_shr:1 row_mask:0xf bank_mask:0xf bound_ctrl:1
	v_add_f32_dpp v135, v99, v135 row_shr:2 row_mask:0xf bank_mask:0xf bound_ctrl:1
	v_cmp_gt_i32_e64 s[12:13], s73, v197
	v_add_u32_e32 v199, s33, v197
	s_and_saveexec_b64 s[14:15], s[12:13]
	s_cbranch_execz .LBB0_1165
	s_waitcnt vmcnt(0)
	v_pk_fma_f32 v[132:133], v[126:127], v[132:133], v[130:131]
	v_pk_fma_f32 v[132:133], v[122:123], v[166:167], v[132:133]
	v_pk_fma_f32 v[148:149], v[124:125], v[148:149], v[128:129]
	v_pk_fma_f32 v[132:133], v[110:111], v[118:119], v[132:133]
	v_pk_fma_f32 v[148:149], v[120:121], v[162:163], v[148:149]
	v_mul_f32_e32 v160, 0xbfb8aa3b, v132
	v_mul_f32_e32 v161, 0xbfb8aa3b, v133
	v_pk_fma_f32 v[148:149], v[108:109], v[116:117], v[148:149]
	v_exp_f32_e32 v160, v160
	v_exp_f32_e32 v161, v161
	v_mul_f32_e32 v150, 0xbfb8aa3b, v148
	v_mul_f32_e32 v151, 0xbfb8aa3b, v149
	v_exp_f32_e32 v150, v150
	v_exp_f32_e32 v151, v151
	v_add_f32_e32 v160, 1.0, v160
	v_add_f32_e32 v161, 1.0, v161
	v_rcp_f32_e32 v160, v160
	v_rcp_f32_e32 v161, v161
	v_add_f32_e32 v150, 1.0, v150
	v_add_f32_e32 v151, 1.0, v151
	v_pk_fma_f32 v[134:135], v[142:143], v[134:135], v[146:147]
	v_rcp_f32_e32 v150, v150
	v_rcp_f32_e32 v151, v151
	v_pk_fma_f32 v[134:135], v[138:139], v[210:211], v[134:135]
	v_pk_fma_f32 v[170:171], v[140:141], v[170:171], v[144:145]
	v_pk_fma_f32 v[134:135], v[98:99], v[114:115], v[134:135]
	v_pk_mul_f32 v[132:133], v[132:133], v[160:161]
	v_pk_fma_f32 v[170:171], v[136:137], v[174:175], v[170:171]
	v_pk_mul_f32 v[132:133], v[134:135], v[132:133]
	v_pk_fma_f32 v[162:163], v[96:97], v[112:113], v[170:171]
	v_pk_mul_f32 v[148:149], v[148:149], v[150:151]
	v_cvt_pk_bf16_f32 v135, v132, v133
	v_mov_b64_e32 v[132:133], s[34:35]
	v_pk_mul_f32 v[148:149], v[162:163], v[148:149]
	v_mad_i64_i32 v[132:133], s[16:17], v199, s92, v[132:133]
	v_cvt_pk_bf16_f32 v134, v148, v149
	v_lshl_add_u64 v[132:133], v[192:193], 1, v[132:133]
	global_store_dwordx2 v[132:133], v[134:135], off
.LBB0_1165:
	s_or_b64 exec, exec, s[14:15]
	v_pk_mul_f32 v[94:95], v[94:95], v[200:201] op_sel_hi:[1,0]
	v_pk_mul_f32 v[92:93], v[92:93], v[200:201] op_sel_hi:[1,0]
	v_pk_mul_f32 v[90:91], v[90:91], v[200:201] op_sel_hi:[1,0]
	v_pk_mul_f32 v[88:89], v[88:89], v[200:201] op_sel_hi:[1,0]
	v_add_u32_e32 v197, s18, v226
	v_mov_b32_dpp v148, v108 row_shl:15 row_mask:0xf bank_mask:0xf bound_ctrl:1
	v_mov_b32_dpp v108, v108 row_shl:14 row_mask:0xf bank_mask:0xf bound_ctrl:1
	v_mov_b32_dpp v168, v96 row_shl:15 row_mask:0xf bank_mask:0xf bound_ctrl:1
	v_mov_b32_dpp v164, v96 row_shl:14 row_mask:0xf bank_mask:0xf bound_ctrl:1
	v_mov_b32_dpp v149, v109 row_shl:15 row_mask:0xf bank_mask:0xf bound_ctrl:1
	v_mov_b32_dpp v109, v109 row_shl:14 row_mask:0xf bank_mask:0xf bound_ctrl:1
	v_mov_b32_dpp v169, v97 row_shl:15 row_mask:0xf bank_mask:0xf bound_ctrl:1
	v_mov_b32_dpp v165, v97 row_shl:14 row_mask:0xf bank_mask:0xf bound_ctrl:1
	v_mov_b32_dpp v160, v110 row_shl:15 row_mask:0xf bank_mask:0xf bound_ctrl:1
	v_mov_b32_dpp v110, v110 row_shl:14 row_mask:0xf bank_mask:0xf bound_ctrl:1
	v_mov_b32_dpp v174, v98 row_shl:15 row_mask:0xf bank_mask:0xf bound_ctrl:1
	v_mov_b32_dpp v98, v98 row_shl:14 row_mask:0xf bank_mask:0xf bound_ctrl:1
	v_mov_b32_dpp v161, v111 row_shl:15 row_mask:0xf bank_mask:0xf bound_ctrl:1
	v_mov_b32_dpp v111, v111 row_shl:14 row_mask:0xf bank_mask:0xf bound_ctrl:1
	v_mov_b32_dpp v175, v99 row_shl:15 row_mask:0xf bank_mask:0xf bound_ctrl:1
	v_mov_b32_dpp v99, v99 row_shl:14 row_mask:0xf bank_mask:0xf bound_ctrl:1
	v_add_f32_dpp v134, v92, v148 row_shr:1 row_mask:0xf bank_mask:0xf bound_ctrl:1
	v_add_f32_dpp v108, v92, v108 row_shr:2 row_mask:0xf bank_mask:0xf bound_ctrl:1
	v_add_f32_dpp v166, v88, v168 row_shr:1 row_mask:0xf bank_mask:0xf bound_ctrl:1
	v_add_f32_dpp v162, v88, v164 row_shr:2 row_mask:0xf bank_mask:0xf bound_ctrl:1
	v_add_f32_dpp v135, v93, v149 row_shr:1 row_mask:0xf bank_mask:0xf bound_ctrl:1
	v_add_f32_dpp v109, v93, v109 row_shr:2 row_mask:0xf bank_mask:0xf bound_ctrl:1
	v_add_f32_dpp v167, v89, v169 row_shr:1 row_mask:0xf bank_mask:0xf bound_ctrl:1
	v_add_f32_dpp v163, v89, v165 row_shr:2 row_mask:0xf bank_mask:0xf bound_ctrl:1
	v_add_f32_dpp v150, v94, v160 row_shr:1 row_mask:0xf bank_mask:0xf bound_ctrl:1
	v_add_f32_dpp v96, v94, v110 row_shr:2 row_mask:0xf bank_mask:0xf bound_ctrl:1
	v_add_f32_dpp v172, v90, v174 row_shr:1 row_mask:0xf bank_mask:0xf bound_ctrl:1
	v_add_f32_dpp v98, v90, v98 row_shr:2 row_mask:0xf bank_mask:0xf bound_ctrl:1
	v_add_f32_dpp v151, v95, v161 row_shr:1 row_mask:0xf bank_mask:0xf bound_ctrl:1
	v_add_f32_dpp v97, v95, v111 row_shr:2 row_mask:0xf bank_mask:0xf bound_ctrl:1
	v_add_f32_dpp v173, v91, v175 row_shr:1 row_mask:0xf bank_mask:0xf bound_ctrl:1
	v_add_f32_dpp v99, v91, v99 row_shr:2 row_mask:0xf bank_mask:0xf bound_ctrl:1
	v_cmp_gt_i32_e64 s[14:15], s73, v197
	v_add_u32_e32 v197, s33, v197
	s_and_saveexec_b64 s[16:17], s[14:15]
	s_cbranch_execz .LBB0_1167
	s_waitcnt vmcnt(0)
	v_pk_fma_f32 v[96:97], v[126:127], v[96:97], v[130:131]
	v_pk_fma_f32 v[96:97], v[122:123], v[150:151], v[96:97]
	v_pk_fma_f32 v[108:109], v[124:125], v[108:109], v[128:129]
	v_pk_fma_f32 v[96:97], v[94:95], v[118:119], v[96:97]
	v_pk_fma_f32 v[108:109], v[120:121], v[134:135], v[108:109]
	v_mul_f32_e32 v132, 0xbfb8aa3b, v96
	v_mul_f32_e32 v133, 0xbfb8aa3b, v97
	v_pk_fma_f32 v[108:109], v[92:93], v[116:117], v[108:109]
	v_exp_f32_e32 v132, v132
	v_exp_f32_e32 v133, v133
	v_mul_f32_e32 v110, 0xbfb8aa3b, v108
	v_mul_f32_e32 v111, 0xbfb8aa3b, v109
	v_exp_f32_e32 v110, v110
	v_exp_f32_e32 v111, v111
	v_add_f32_e32 v132, 1.0, v132
	v_add_f32_e32 v133, 1.0, v133
	v_rcp_f32_e32 v132, v132
	v_rcp_f32_e32 v133, v133
	v_add_f32_e32 v110, 1.0, v110
	v_add_f32_e32 v111, 1.0, v111
	v_pk_fma_f32 v[98:99], v[142:143], v[98:99], v[146:147]
	v_rcp_f32_e32 v110, v110
	v_rcp_f32_e32 v111, v111
	v_pk_fma_f32 v[98:99], v[138:139], v[172:173], v[98:99]
	v_pk_fma_f32 v[162:163], v[140:141], v[162:163], v[144:145]
	v_pk_fma_f32 v[98:99], v[90:91], v[114:115], v[98:99]
	v_pk_mul_f32 v[96:97], v[96:97], v[132:133]
	v_pk_fma_f32 v[162:163], v[136:137], v[166:167], v[162:163]
	v_pk_mul_f32 v[96:97], v[98:99], v[96:97]
	v_pk_fma_f32 v[134:135], v[88:89], v[112:113], v[162:163]
	v_pk_mul_f32 v[108:109], v[108:109], v[110:111]
	v_cvt_pk_bf16_f32 v99, v96, v97
	v_mov_b64_e32 v[96:97], s[34:35]
	v_pk_mul_f32 v[108:109], v[134:135], v[108:109]
	v_mad_i64_i32 v[96:97], s[22:23], v197, s92, v[96:97]
	v_cvt_pk_bf16_f32 v98, v108, v109
	v_lshl_add_u64 v[96:97], v[192:193], 1, v[96:97]
	global_store_dwordx2 v[96:97], v[98:99], off
.LBB0_1167:
	s_or_b64 exec, exec, s[16:17]
	v_add_u32_e32 v168, s18, v227
	v_mov_b32_dpp v108, v92 row_shl:15 row_mask:0xf bank_mask:0xf bound_ctrl:1
	v_mov_b32_dpp v92, v92 row_shl:14 row_mask:0xf bank_mask:0xf bound_ctrl:1
	v_mov_b32_dpp v160, v88 row_shl:15 row_mask:0xf bank_mask:0xf bound_ctrl:1
	v_mov_b32_dpp v148, v88 row_shl:14 row_mask:0xf bank_mask:0xf bound_ctrl:1
	v_mov_b32_dpp v109, v93 row_shl:15 row_mask:0xf bank_mask:0xf bound_ctrl:1
	v_mov_b32_dpp v93, v93 row_shl:14 row_mask:0xf bank_mask:0xf bound_ctrl:1
	v_mov_b32_dpp v161, v89 row_shl:15 row_mask:0xf bank_mask:0xf bound_ctrl:1
	v_mov_b32_dpp v149, v89 row_shl:14 row_mask:0xf bank_mask:0xf bound_ctrl:1
	v_mov_b32_dpp v132, v94 row_shl:15 row_mask:0xf bank_mask:0xf bound_ctrl:1
	v_mov_b32_dpp v94, v94 row_shl:14 row_mask:0xf bank_mask:0xf bound_ctrl:1
	v_mov_b32_dpp v166, v90 row_shl:15 row_mask:0xf bank_mask:0xf bound_ctrl:1
	v_mov_b32_dpp v90, v90 row_shl:14 row_mask:0xf bank_mask:0xf bound_ctrl:1
	v_mov_b32_dpp v133, v95 row_shl:15 row_mask:0xf bank_mask:0xf bound_ctrl:1
	v_mov_b32_dpp v95, v95 row_shl:14 row_mask:0xf bank_mask:0xf bound_ctrl:1
	v_mov_b32_dpp v167, v91 row_shl:15 row_mask:0xf bank_mask:0xf bound_ctrl:1
	v_mov_b32_dpp v91, v91 row_shl:14 row_mask:0xf bank_mask:0xf bound_ctrl:1
	v_add_f32_dpp v98, v156, v108 row_shr:1 row_mask:0xf bank_mask:0xf bound_ctrl:1
	v_add_f32_dpp v92, v156, v92 row_shr:2 row_mask:0xf bank_mask:0xf bound_ctrl:1
	v_add_f32_dpp v150, v152, v160 row_shr:1 row_mask:0xf bank_mask:0xf bound_ctrl:1
	v_add_f32_dpp v134, v152, v148 row_shr:2 row_mask:0xf bank_mask:0xf bound_ctrl:1
	v_add_f32_dpp v99, v157, v109 row_shr:1 row_mask:0xf bank_mask:0xf bound_ctrl:1
	v_add_f32_dpp v93, v157, v93 row_shr:2 row_mask:0xf bank_mask:0xf bound_ctrl:1
	v_add_f32_dpp v151, v153, v161 row_shr:1 row_mask:0xf bank_mask:0xf bound_ctrl:1
	v_add_f32_dpp v135, v153, v149 row_shr:2 row_mask:0xf bank_mask:0xf bound_ctrl:1
	v_add_f32_dpp v110, v158, v132 row_shr:1 row_mask:0xf bank_mask:0xf bound_ctrl:1
	v_add_f32_dpp v88, v158, v94 row_shr:2 row_mask:0xf bank_mask:0xf bound_ctrl:1
	v_add_f32_dpp v164, v154, v166 row_shr:1 row_mask:0xf bank_mask:0xf bound_ctrl:1
	v_add_f32_dpp v90, v154, v90 row_shr:2 row_mask:0xf bank_mask:0xf bound_ctrl:1
	v_add_f32_dpp v111, v159, v133 row_shr:1 row_mask:0xf bank_mask:0xf bound_ctrl:1
	v_add_f32_dpp v89, v159, v95 row_shr:2 row_mask:0xf bank_mask:0xf bound_ctrl:1
	v_add_f32_dpp v165, v155, v167 row_shr:1 row_mask:0xf bank_mask:0xf bound_ctrl:1
	v_add_f32_dpp v91, v155, v91 row_shr:2 row_mask:0xf bank_mask:0xf bound_ctrl:1
	v_cmp_gt_i32_e64 s[22:23], s73, v168
	v_add_u32_e32 v168, s33, v168
	s_and_saveexec_b64 s[16:17], s[22:23]
	s_cbranch_execz .LBB0_1169
	s_waitcnt vmcnt(0)
	v_pk_fma_f32 v[88:89], v[126:127], v[88:89], v[130:131]
	v_pk_fma_f32 v[88:89], v[122:123], v[110:111], v[88:89]
	v_pk_fma_f32 v[92:93], v[124:125], v[92:93], v[128:129]
	v_pk_fma_f32 v[88:89], v[158:159], v[118:119], v[88:89]
	v_pk_fma_f32 v[92:93], v[120:121], v[98:99], v[92:93]
	v_mul_f32_e32 v96, 0xbfb8aa3b, v88
	v_mul_f32_e32 v97, 0xbfb8aa3b, v89
	v_pk_fma_f32 v[92:93], v[156:157], v[116:117], v[92:93]
	v_exp_f32_e32 v96, v96
	v_exp_f32_e32 v97, v97
	v_mul_f32_e32 v94, 0xbfb8aa3b, v92
	v_mul_f32_e32 v95, 0xbfb8aa3b, v93
	v_exp_f32_e32 v94, v94
	v_exp_f32_e32 v95, v95
	v_add_f32_e32 v96, 1.0, v96
	v_add_f32_e32 v97, 1.0, v97
	v_rcp_f32_e32 v96, v96
	v_rcp_f32_e32 v97, v97
	v_add_f32_e32 v94, 1.0, v94
	v_add_f32_e32 v95, 1.0, v95
	v_pk_fma_f32 v[90:91], v[142:143], v[90:91], v[146:147]
	v_rcp_f32_e32 v94, v94
	v_rcp_f32_e32 v95, v95
	v_pk_fma_f32 v[90:91], v[138:139], v[164:165], v[90:91]
	v_pk_fma_f32 v[134:135], v[140:141], v[134:135], v[144:145]
	v_pk_fma_f32 v[90:91], v[154:155], v[114:115], v[90:91]
	v_pk_mul_f32 v[88:89], v[88:89], v[96:97]
	v_pk_fma_f32 v[134:135], v[136:137], v[150:151], v[134:135]
	v_pk_mul_f32 v[88:89], v[90:91], v[88:89]
	v_pk_fma_f32 v[98:99], v[152:153], v[112:113], v[134:135]
	v_pk_mul_f32 v[92:93], v[92:93], v[94:95]
	v_cvt_pk_bf16_f32 v91, v88, v89
	v_mov_b64_e32 v[88:89], s[34:35]
	v_pk_mul_f32 v[92:93], v[98:99], v[92:93]
	v_mad_i64_i32 v[88:89], s[18:19], v168, s92, v[88:89]
	v_cvt_pk_bf16_f32 v90, v92, v93
	v_lshl_add_u64 v[88:89], v[192:193], 1, v[88:89]
	global_store_dwordx2 v[88:89], v[90:91], off

.LBB0_1177:
	s_or_b64 exec, exec, s[16:17]
	v_pk_mul_f32 v[70:71], v[70:71], v[196:197] op_sel_hi:[1,0]
	v_pk_mul_f32 v[68:69], v[68:69], v[196:197] op_sel_hi:[1,0]
	v_pk_mul_f32 v[66:67], v[66:67], v[196:197] op_sel_hi:[1,0]
	v_pk_mul_f32 v[64:65], v[64:65], v[196:197] op_sel_hi:[1,0]
	s_waitcnt lgkmcnt(0)
	v_mov_b32_dpp v92, v84 row_shl:15 row_mask:0xf bank_mask:0xf bound_ctrl:1
	v_mov_b32_dpp v84, v84 row_shl:14 row_mask:0xf bank_mask:0xf bound_ctrl:1
	v_mov_b32_dpp v132, v80 row_shl:15 row_mask:0xf bank_mask:0xf bound_ctrl:1
	v_mov_b32_dpp v108, v80 row_shl:14 row_mask:0xf bank_mask:0xf bound_ctrl:1
	v_mov_b32_dpp v93, v85 row_shl:15 row_mask:0xf bank_mask:0xf bound_ctrl:1
	v_mov_b32_dpp v85, v85 row_shl:14 row_mask:0xf bank_mask:0xf bound_ctrl:1
	v_mov_b32_dpp v133, v81 row_shl:15 row_mask:0xf bank_mask:0xf bound_ctrl:1
	v_mov_b32_dpp v109, v81 row_shl:14 row_mask:0xf bank_mask:0xf bound_ctrl:1
	v_mov_b32_dpp v96, v86 row_shl:15 row_mask:0xf bank_mask:0xf bound_ctrl:1
	v_mov_b32_dpp v86, v86 row_shl:14 row_mask:0xf bank_mask:0xf bound_ctrl:1
	v_mov_b32_dpp v150, v82 row_shl:15 row_mask:0xf bank_mask:0xf bound_ctrl:1
	v_mov_b32_dpp v82, v82 row_shl:14 row_mask:0xf bank_mask:0xf bound_ctrl:1
	v_mov_b32_dpp v97, v87 row_shl:15 row_mask:0xf bank_mask:0xf bound_ctrl:1
	v_mov_b32_dpp v87, v87 row_shl:14 row_mask:0xf bank_mask:0xf bound_ctrl:1
	v_mov_b32_dpp v151, v83 row_shl:15 row_mask:0xf bank_mask:0xf bound_ctrl:1
	v_mov_b32_dpp v83, v83 row_shl:14 row_mask:0xf bank_mask:0xf bound_ctrl:1
	v_add_f32_dpp v90, v68, v92 row_shr:1 row_mask:0xf bank_mask:0xf bound_ctrl:1
	v_add_f32_dpp v84, v68, v84 row_shr:2 row_mask:0xf bank_mask:0xf bound_ctrl:1
	v_add_f32_dpp v110, v64, v132 row_shr:1 row_mask:0xf bank_mask:0xf bound_ctrl:1
	v_add_f32_dpp v98, v64, v108 row_shr:2 row_mask:0xf bank_mask:0xf bound_ctrl:1
	v_add_f32_dpp v91, v69, v93 row_shr:1 row_mask:0xf bank_mask:0xf bound_ctrl:1
	v_add_f32_dpp v85, v69, v85 row_shr:2 row_mask:0xf bank_mask:0xf bound_ctrl:1
	v_add_f32_dpp v111, v65, v133 row_shr:1 row_mask:0xf bank_mask:0xf bound_ctrl:1
	v_add_f32_dpp v99, v65, v109 row_shr:2 row_mask:0xf bank_mask:0xf bound_ctrl:1
	v_add_f32_dpp v94, v70, v96 row_shr:1 row_mask:0xf bank_mask:0xf bound_ctrl:1
	v_add_f32_dpp v80, v70, v86 row_shr:2 row_mask:0xf bank_mask:0xf bound_ctrl:1
	v_add_f32_dpp v148, v66, v150 row_shr:1 row_mask:0xf bank_mask:0xf bound_ctrl:1
	v_add_f32_dpp v82, v66, v82 row_shr:2 row_mask:0xf bank_mask:0xf bound_ctrl:1
	v_add_f32_dpp v95, v71, v97 row_shr:1 row_mask:0xf bank_mask:0xf bound_ctrl:1
	v_add_f32_dpp v81, v71, v87 row_shr:2 row_mask:0xf bank_mask:0xf bound_ctrl:1
	v_add_f32_dpp v149, v67, v151 row_shr:1 row_mask:0xf bank_mask:0xf bound_ctrl:1
	v_add_f32_dpp v83, v67, v83 row_shr:2 row_mask:0xf bank_mask:0xf bound_ctrl:1
	v_cmp_gt_i32_e64 s[18:19], s73, v240
	v_add_u32_e32 v152, s33, v240
	s_and_saveexec_b64 s[16:17], s[18:19]
	s_cbranch_execz .LBB0_1179
	s_waitcnt vmcnt(0)
	v_pk_fma_f32 v[80:81], v[126:127], v[80:81], v[130:131]
	v_pk_fma_f32 v[80:81], v[122:123], v[94:95], v[80:81]
	v_pk_fma_f32 v[84:85], v[124:125], v[84:85], v[128:129]
	v_pk_fma_f32 v[80:81], v[70:71], v[118:119], v[80:81]
	v_pk_fma_f32 v[84:85], v[120:121], v[90:91], v[84:85]
	v_mul_f32_e32 v88, 0xbfb8aa3b, v80
	v_mul_f32_e32 v89, 0xbfb8aa3b, v81
	v_pk_fma_f32 v[84:85], v[68:69], v[116:117], v[84:85]
	v_exp_f32_e32 v88, v88
	v_exp_f32_e32 v89, v89
	v_mul_f32_e32 v86, 0xbfb8aa3b, v84
	v_mul_f32_e32 v87, 0xbfb8aa3b, v85
	v_exp_f32_e32 v86, v86
	v_exp_f32_e32 v87, v87
	v_add_f32_e32 v88, 1.0, v88
	v_add_f32_e32 v89, 1.0, v89
	v_rcp_f32_e32 v88, v88
	v_rcp_f32_e32 v89, v89
	v_add_f32_e32 v86, 1.0, v86
	v_add_f32_e32 v87, 1.0, v87
	v_pk_fma_f32 v[82:83], v[142:143], v[82:83], v[146:147]
	v_rcp_f32_e32 v86, v86
	v_rcp_f32_e32 v87, v87
	v_pk_fma_f32 v[82:83], v[138:139], v[148:149], v[82:83]
	v_pk_fma_f32 v[98:99], v[140:141], v[98:99], v[144:145]
	v_pk_fma_f32 v[82:83], v[66:67], v[114:115], v[82:83]
	v_pk_mul_f32 v[80:81], v[80:81], v[88:89]
	v_pk_fma_f32 v[98:99], v[136:137], v[110:111], v[98:99]
	v_pk_mul_f32 v[80:81], v[82:83], v[80:81]
	v_pk_fma_f32 v[90:91], v[64:65], v[112:113], v[98:99]
	v_pk_mul_f32 v[84:85], v[84:85], v[86:87]
	v_cvt_pk_bf16_f32 v83, v80, v81
	v_mov_b64_e32 v[80:81], s[34:35]
	v_pk_mul_f32 v[84:85], v[90:91], v[84:85]
	v_mad_i64_i32 v[80:81], s[26:27], v152, s92, v[80:81]
	v_cvt_pk_bf16_f32 v82, v84, v85
	v_lshl_add_u64 v[80:81], v[192:193], 1, v[80:81]
	global_store_dwordx2 v[80:81], v[82:83], off
.LBB0_1179:
	s_or_b64 exec, exec, s[16:17]
	v_pk_mul_f32 v[62:63], v[62:63], v[194:195] op_sel_hi:[1,0]
	v_pk_mul_f32 v[60:61], v[60:61], v[194:195] op_sel_hi:[1,0]
	v_pk_mul_f32 v[58:59], v[58:59], v[194:195] op_sel_hi:[1,0]
	v_pk_mul_f32 v[56:57], v[56:57], v[194:195] op_sel_hi:[1,0]
	v_mov_b32_dpp v84, v68 row_shl:15 row_mask:0xf bank_mask:0xf bound_ctrl:1
	v_mov_b32_dpp v68, v68 row_shl:14 row_mask:0xf bank_mask:0xf bound_ctrl:1
	v_mov_b32_dpp v96, v64 row_shl:15 row_mask:0xf bank_mask:0xf bound_ctrl:1
	v_mov_b32_dpp v92, v64 row_shl:14 row_mask:0xf bank_mask:0xf bound_ctrl:1
	v_mov_b32_dpp v85, v69 row_shl:15 row_mask:0xf bank_mask:0xf bound_ctrl:1
	v_mov_b32_dpp v69, v69 row_shl:14 row_mask:0xf bank_mask:0xf bound_ctrl:1
	v_mov_b32_dpp v97, v65 row_shl:15 row_mask:0xf bank_mask:0xf bound_ctrl:1
	v_mov_b32_dpp v93, v65 row_shl:14 row_mask:0xf bank_mask:0xf bound_ctrl:1
	v_mov_b32_dpp v88, v70 row_shl:15 row_mask:0xf bank_mask:0xf bound_ctrl:1
	v_mov_b32_dpp v70, v70 row_shl:14 row_mask:0xf bank_mask:0xf bound_ctrl:1
	v_mov_b32_dpp v110, v66 row_shl:15 row_mask:0xf bank_mask:0xf bound_ctrl:1
	v_mov_b32_dpp v66, v66 row_shl:14 row_mask:0xf bank_mask:0xf bound_ctrl:1
	v_mov_b32_dpp v89, v71 row_shl:15 row_mask:0xf bank_mask:0xf bound_ctrl:1
	v_mov_b32_dpp v71, v71 row_shl:14 row_mask:0xf bank_mask:0xf bound_ctrl:1
	v_mov_b32_dpp v111, v67 row_shl:15 row_mask:0xf bank_mask:0xf bound_ctrl:1
	v_mov_b32_dpp v67, v67 row_shl:14 row_mask:0xf bank_mask:0xf bound_ctrl:1
	v_add_f32_dpp v82, v60, v84 row_shr:1 row_mask:0xf bank_mask:0xf bound_ctrl:1
	v_add_f32_dpp v68, v60, v68 row_shr:2 row_mask:0xf bank_mask:0xf bound_ctrl:1
	v_add_f32_dpp v94, v56, v96 row_shr:1 row_mask:0xf bank_mask:0xf bound_ctrl:1
	v_add_f32_dpp v90, v56, v92 row_shr:2 row_mask:0xf bank_mask:0xf bound_ctrl:1
	v_add_f32_dpp v83, v61, v85 row_shr:1 row_mask:0xf bank_mask:0xf bound_ctrl:1
	v_add_f32_dpp v69, v61, v69 row_shr:2 row_mask:0xf bank_mask:0xf bound_ctrl:1
	v_add_f32_dpp v95, v57, v97 row_shr:1 row_mask:0xf bank_mask:0xf bound_ctrl:1
	v_add_f32_dpp v91, v57, v93 row_shr:2 row_mask:0xf bank_mask:0xf bound_ctrl:1
	v_add_f32_dpp v86, v62, v88 row_shr:1 row_mask:0xf bank_mask:0xf bound_ctrl:1
	v_add_f32_dpp v64, v62, v70 row_shr:2 row_mask:0xf bank_mask:0xf bound_ctrl:1
	v_add_f32_dpp v108, v58, v110 row_shr:1 row_mask:0xf bank_mask:0xf bound_ctrl:1
	v_add_f32_dpp v66, v58, v66 row_shr:2 row_mask:0xf bank_mask:0xf bound_ctrl:1
	v_add_f32_dpp v87, v63, v89 row_shr:1 row_mask:0xf bank_mask:0xf bound_ctrl:1
	v_add_f32_dpp v65, v63, v71 row_shr:2 row_mask:0xf bank_mask:0xf bound_ctrl:1
	v_add_f32_dpp v109, v59, v111 row_shr:1 row_mask:0xf bank_mask:0xf bound_ctrl:1
	v_add_f32_dpp v67, v59, v67 row_shr:2 row_mask:0xf bank_mask:0xf bound_ctrl:1
	v_cmp_gt_i32_e64 s[16:17], s73, v205
	v_add_u32_e32 v132, s33, v205
	s_and_saveexec_b64 s[26:27], s[16:17]
	s_cbranch_execz .LBB0_1181
	s_waitcnt vmcnt(0)
	v_pk_fma_f32 v[64:65], v[126:127], v[64:65], v[130:131]
	v_pk_fma_f32 v[64:65], v[122:123], v[86:87], v[64:65]
	v_pk_fma_f32 v[68:69], v[124:125], v[68:69], v[128:129]
	v_pk_fma_f32 v[64:65], v[62:63], v[118:119], v[64:65]
	v_pk_fma_f32 v[68:69], v[120:121], v[82:83], v[68:69]
	v_mul_f32_e32 v80, 0xbfb8aa3b, v64
	v_mul_f32_e32 v81, 0xbfb8aa3b, v65
	v_pk_fma_f32 v[68:69], v[60:61], v[116:117], v[68:69]
	v_exp_f32_e32 v80, v80
	v_exp_f32_e32 v81, v81
	v_mul_f32_e32 v70, 0xbfb8aa3b, v68
	v_mul_f32_e32 v71, 0xbfb8aa3b, v69
	v_exp_f32_e32 v70, v70
	v_exp_f32_e32 v71, v71
	v_add_f32_e32 v80, 1.0, v80
	v_add_f32_e32 v81, 1.0, v81
	v_rcp_f32_e32 v80, v80
	v_rcp_f32_e32 v81, v81
	v_add_f32_e32 v70, 1.0, v70
	v_add_f32_e32 v71, 1.0, v71
	v_pk_fma_f32 v[66:67], v[142:143], v[66:67], v[146:147]
	v_rcp_f32_e32 v70, v70
	v_rcp_f32_e32 v71, v71
	v_pk_fma_f32 v[66:67], v[138:139], v[108:109], v[66:67]
	v_pk_fma_f32 v[90:91], v[140:141], v[90:91], v[144:145]
	v_pk_fma_f32 v[66:67], v[58:59], v[114:115], v[66:67]
	v_pk_mul_f32 v[64:65], v[64:65], v[80:81]
	v_pk_fma_f32 v[90:91], v[136:137], v[94:95], v[90:91]
	v_pk_mul_f32 v[64:65], v[66:67], v[64:65]
	v_pk_fma_f32 v[82:83], v[56:57], v[112:113], v[90:91]
	v_pk_mul_f32 v[68:69], v[68:69], v[70:71]
	v_cvt_pk_bf16_f32 v67, v64, v65
	v_mov_b64_e32 v[64:65], s[34:35]
	v_pk_mul_f32 v[68:69], v[82:83], v[68:69]
	v_mad_i64_i32 v[64:65], s[64:65], v132, s92, v[64:65]
	v_cvt_pk_bf16_f32 v66, v68, v69
	v_lshl_add_u64 v[64:65], v[192:193], 1, v[64:65]
	global_store_dwordx2 v[64:65], v[66:67], off
.LBB0_1181:
	s_or_b64 exec, exec, s[26:27]
	v_mov_b32_dpp v68, v60 row_shl:15 row_mask:0xf bank_mask:0xf bound_ctrl:1
	v_mov_b32_dpp v60, v60 row_shl:14 row_mask:0xf bank_mask:0xf bound_ctrl:1
	v_mov_b32_dpp v88, v56 row_shl:15 row_mask:0xf bank_mask:0xf bound_ctrl:1
	v_mov_b32_dpp v84, v56 row_shl:14 row_mask:0xf bank_mask:0xf bound_ctrl:1
	v_mov_b32_dpp v69, v61 row_shl:15 row_mask:0xf bank_mask:0xf bound_ctrl:1
	v_mov_b32_dpp v61, v61 row_shl:14 row_mask:0xf bank_mask:0xf bound_ctrl:1
	v_mov_b32_dpp v89, v57 row_shl:15 row_mask:0xf bank_mask:0xf bound_ctrl:1
	v_mov_b32_dpp v85, v57 row_shl:14 row_mask:0xf bank_mask:0xf bound_ctrl:1
	v_mov_b32_dpp v80, v62 row_shl:15 row_mask:0xf bank_mask:0xf bound_ctrl:1
	v_mov_b32_dpp v62, v62 row_shl:14 row_mask:0xf bank_mask:0xf bound_ctrl:1
	v_mov_b32_dpp v94, v58 row_shl:15 row_mask:0xf bank_mask:0xf bound_ctrl:1
	v_mov_b32_dpp v58, v58 row_shl:14 row_mask:0xf bank_mask:0xf bound_ctrl:1
	v_mov_b32_dpp v81, v63 row_shl:15 row_mask:0xf bank_mask:0xf bound_ctrl:1
	v_mov_b32_dpp v63, v63 row_shl:14 row_mask:0xf bank_mask:0xf bound_ctrl:1
	v_mov_b32_dpp v95, v59 row_shl:15 row_mask:0xf bank_mask:0xf bound_ctrl:1
	v_mov_b32_dpp v59, v59 row_shl:14 row_mask:0xf bank_mask:0xf bound_ctrl:1
	v_add_f32_dpp v66, v104, v68 row_shr:1 row_mask:0xf bank_mask:0xf bound_ctrl:1
	v_add_f32_dpp v60, v104, v60 row_shr:2 row_mask:0xf bank_mask:0xf bound_ctrl:1
	v_add_f32_dpp v86, v100, v88 row_shr:1 row_mask:0xf bank_mask:0xf bound_ctrl:1
	v_add_f32_dpp v82, v100, v84 row_shr:2 row_mask:0xf bank_mask:0xf bound_ctrl:1
	v_add_f32_dpp v67, v105, v69 row_shr:1 row_mask:0xf bank_mask:0xf bound_ctrl:1
	v_add_f32_dpp v61, v105, v61 row_shr:2 row_mask:0xf bank_mask:0xf bound_ctrl:1
	v_add_f32_dpp v87, v101, v89 row_shr:1 row_mask:0xf bank_mask:0xf bound_ctrl:1
	v_add_f32_dpp v83, v101, v85 row_shr:2 row_mask:0xf bank_mask:0xf bound_ctrl:1
	v_add_f32_dpp v70, v106, v80 row_shr:1 row_mask:0xf bank_mask:0xf bound_ctrl:1
	v_add_f32_dpp v56, v106, v62 row_shr:2 row_mask:0xf bank_mask:0xf bound_ctrl:1
	v_add_f32_dpp v92, v102, v94 row_shr:1 row_mask:0xf bank_mask:0xf bound_ctrl:1
	v_add_f32_dpp v58, v102, v58 row_shr:2 row_mask:0xf bank_mask:0xf bound_ctrl:1
	v_add_f32_dpp v71, v107, v81 row_shr:1 row_mask:0xf bank_mask:0xf bound_ctrl:1
	v_add_f32_dpp v57, v107, v63 row_shr:2 row_mask:0xf bank_mask:0xf bound_ctrl:1
	v_add_f32_dpp v93, v103, v95 row_shr:1 row_mask:0xf bank_mask:0xf bound_ctrl:1
	v_add_f32_dpp v59, v103, v59 row_shr:2 row_mask:0xf bank_mask:0xf bound_ctrl:1
	v_cmp_gt_i32_e64 s[26:27], s73, v203
	v_add_u32_e32 v133, s33, v203
	s_and_saveexec_b64 s[64:65], s[26:27]
	s_cbranch_execz .LBB0_1183
	s_waitcnt vmcnt(0)
	v_pk_fma_f32 v[56:57], v[126:127], v[56:57], v[130:131]
	v_pk_fma_f32 v[56:57], v[122:123], v[70:71], v[56:57]
	v_pk_fma_f32 v[60:61], v[124:125], v[60:61], v[128:129]
	v_pk_fma_f32 v[56:57], v[106:107], v[118:119], v[56:57]
	v_pk_fma_f32 v[60:61], v[120:121], v[66:67], v[60:61]
	v_mul_f32_e32 v64, 0xbfb8aa3b, v56
	v_mul_f32_e32 v65, 0xbfb8aa3b, v57
	v_pk_fma_f32 v[60:61], v[104:105], v[116:117], v[60:61]
	v_exp_f32_e32 v64, v64
	v_exp_f32_e32 v65, v65
	v_mul_f32_e32 v62, 0xbfb8aa3b, v60
	v_mul_f32_e32 v63, 0xbfb8aa3b, v61
	v_exp_f32_e32 v62, v62
	v_exp_f32_e32 v63, v63
	v_add_f32_e32 v64, 1.0, v64
	v_add_f32_e32 v65, 1.0, v65
	v_rcp_f32_e32 v64, v64
	v_rcp_f32_e32 v65, v65
	v_add_f32_e32 v62, 1.0, v62
	v_add_f32_e32 v63, 1.0, v63
	v_pk_fma_f32 v[58:59], v[142:143], v[58:59], v[146:147]
	v_rcp_f32_e32 v62, v62
	v_rcp_f32_e32 v63, v63
	v_pk_fma_f32 v[58:59], v[138:139], v[92:93], v[58:59]
	v_pk_fma_f32 v[82:83], v[140:141], v[82:83], v[144:145]
	v_pk_fma_f32 v[58:59], v[102:103], v[114:115], v[58:59]
	v_pk_mul_f32 v[56:57], v[56:57], v[64:65]
	v_pk_fma_f32 v[82:83], v[136:137], v[86:87], v[82:83]
	v_pk_mul_f32 v[56:57], v[58:59], v[56:57]
	v_pk_fma_f32 v[66:67], v[100:101], v[112:113], v[82:83]
	v_pk_mul_f32 v[60:61], v[60:61], v[62:63]
	v_cvt_pk_bf16_f32 v59, v56, v57
	v_mov_b64_e32 v[56:57], s[34:35]
	v_pk_mul_f32 v[60:61], v[66:67], v[60:61]
	v_mad_i64_i32 v[56:57], s[90:91], v133, s92, v[56:57]
	v_cvt_pk_bf16_f32 v58, v60, v61
	v_lshl_add_u64 v[56:57], v[192:193], 1, v[56:57]
	global_store_dwordx2 v[56:57], v[58:59], off

.LBB0_1193:
	s_or_b64 exec, exec, s[20:21]
	v_mov_b32_e32 v203, v202
	v_mov_b32_e32 v96, v202
	v_mov_b32_e32 v97, v202
	v_pk_mul_f32 v[38:39], v[38:39], v[96:97]
	v_pk_mul_f32 v[36:37], v[36:37], v[202:203]
	v_pk_mul_f32 v[34:35], v[34:35], v[96:97]
	v_pk_mul_f32 v[32:33], v[32:33], v[202:203]
	v_mov_b32_dpp v100, v52 row_shl:15 row_mask:0xf bank_mask:0xf bound_ctrl:1
	v_mov_b32_dpp v52, v52 row_shl:14 row_mask:0xf bank_mask:0xf bound_ctrl:1
	v_mov_b32_dpp v112, v48 row_shl:15 row_mask:0xf bank_mask:0xf bound_ctrl:1
	v_mov_b32_dpp v108, v48 row_shl:14 row_mask:0xf bank_mask:0xf bound_ctrl:1
	v_mov_b32_dpp v101, v53 row_shl:15 row_mask:0xf bank_mask:0xf bound_ctrl:1
	v_mov_b32_dpp v53, v53 row_shl:14 row_mask:0xf bank_mask:0xf bound_ctrl:1
	v_mov_b32_dpp v113, v49 row_shl:15 row_mask:0xf bank_mask:0xf bound_ctrl:1
	v_mov_b32_dpp v109, v49 row_shl:14 row_mask:0xf bank_mask:0xf bound_ctrl:1
	v_mov_b32_dpp v104, v54 row_shl:15 row_mask:0xf bank_mask:0xf bound_ctrl:1
	v_mov_b32_dpp v54, v54 row_shl:14 row_mask:0xf bank_mask:0xf bound_ctrl:1
	v_mov_b32_dpp v118, v50 row_shl:15 row_mask:0xf bank_mask:0xf bound_ctrl:1
	v_mov_b32_dpp v50, v50 row_shl:14 row_mask:0xf bank_mask:0xf bound_ctrl:1
	v_mov_b32_dpp v105, v55 row_shl:15 row_mask:0xf bank_mask:0xf bound_ctrl:1
	v_mov_b32_dpp v55, v55 row_shl:14 row_mask:0xf bank_mask:0xf bound_ctrl:1
	v_mov_b32_dpp v119, v51 row_shl:15 row_mask:0xf bank_mask:0xf bound_ctrl:1
	v_mov_b32_dpp v51, v51 row_shl:14 row_mask:0xf bank_mask:0xf bound_ctrl:1
	v_add_f32_dpp v98, v36, v100 row_shr:1 row_mask:0xf bank_mask:0xf bound_ctrl:1
	v_add_f32_dpp v52, v36, v52 row_shr:2 row_mask:0xf bank_mask:0xf bound_ctrl:1
	v_add_f32_dpp v110, v32, v112 row_shr:1 row_mask:0xf bank_mask:0xf bound_ctrl:1
	v_add_f32_dpp v106, v32, v108 row_shr:2 row_mask:0xf bank_mask:0xf bound_ctrl:1
	v_add_f32_dpp v99, v37, v101 row_shr:1 row_mask:0xf bank_mask:0xf bound_ctrl:1
	v_add_f32_dpp v53, v37, v53 row_shr:2 row_mask:0xf bank_mask:0xf bound_ctrl:1
	v_add_f32_dpp v111, v33, v113 row_shr:1 row_mask:0xf bank_mask:0xf bound_ctrl:1
	v_add_f32_dpp v107, v33, v109 row_shr:2 row_mask:0xf bank_mask:0xf bound_ctrl:1
	v_add_f32_dpp v102, v38, v104 row_shr:1 row_mask:0xf bank_mask:0xf bound_ctrl:1
	v_add_f32_dpp v48, v38, v54 row_shr:2 row_mask:0xf bank_mask:0xf bound_ctrl:1
	v_add_f32_dpp v116, v34, v118 row_shr:1 row_mask:0xf bank_mask:0xf bound_ctrl:1
	v_add_f32_dpp v50, v34, v50 row_shr:2 row_mask:0xf bank_mask:0xf bound_ctrl:1
	v_add_f32_dpp v103, v39, v105 row_shr:1 row_mask:0xf bank_mask:0xf bound_ctrl:1
	v_add_f32_dpp v49, v39, v55 row_shr:2 row_mask:0xf bank_mask:0xf bound_ctrl:1
	v_add_f32_dpp v117, v35, v119 row_shr:1 row_mask:0xf bank_mask:0xf bound_ctrl:1
	v_add_f32_dpp v51, v35, v51 row_shr:2 row_mask:0xf bank_mask:0xf bound_ctrl:1
	s_and_saveexec_b64 s[0:1], s[12:13]
	s_cbranch_execz .LBB0_1195
	v_pk_fma_f32 v[48:49], v[70:71], v[48:49], v[82:83]
	v_pk_fma_f32 v[48:49], v[66:67], v[102:103], v[48:49]
	v_pk_fma_f32 v[52:53], v[68:69], v[52:53], v[80:81]
	v_pk_fma_f32 v[48:49], v[38:39], v[62:63], v[48:49]
	v_pk_fma_f32 v[52:53], v[64:65], v[98:99], v[52:53]
	v_mul_f32_e32 v96, 0xbfb8aa3b, v48
	v_mul_f32_e32 v97, 0xbfb8aa3b, v49
	v_pk_fma_f32 v[52:53], v[36:37], v[60:61], v[52:53]
	v_exp_f32_e32 v96, v96
	v_exp_f32_e32 v97, v97
	v_mul_f32_e32 v54, 0xbfb8aa3b, v52
	v_mul_f32_e32 v55, 0xbfb8aa3b, v53
	v_exp_f32_e32 v54, v54
	v_exp_f32_e32 v55, v55
	v_add_f32_e32 v96, 1.0, v96
	v_add_f32_e32 v97, 1.0, v97
	v_rcp_f32_e32 v96, v96
	v_rcp_f32_e32 v97, v97
	v_add_f32_e32 v54, 1.0, v54
	v_add_f32_e32 v55, 1.0, v55
	v_pk_fma_f32 v[50:51], v[90:91], v[50:51], v[94:95]
	v_rcp_f32_e32 v54, v54
	v_rcp_f32_e32 v55, v55
	v_pk_fma_f32 v[50:51], v[86:87], v[116:117], v[50:51]
	v_pk_fma_f32 v[106:107], v[88:89], v[106:107], v[92:93]
	v_pk_fma_f32 v[50:51], v[34:35], v[58:59], v[50:51]
	v_pk_mul_f32 v[48:49], v[48:49], v[96:97]
	v_pk_fma_f32 v[106:107], v[84:85], v[110:111], v[106:107]
	v_pk_mul_f32 v[48:49], v[50:51], v[48:49]
	v_pk_fma_f32 v[98:99], v[32:33], v[56:57], v[106:107]
	v_pk_mul_f32 v[52:53], v[52:53], v[54:55]
	v_cvt_pk_bf16_f32 v51, v48, v49
	v_mov_b64_e32 v[48:49], s[34:35]
	v_pk_mul_f32 v[52:53], v[98:99], v[52:53]
	v_mad_i64_i32 v[48:49], s[12:13], v199, s92, v[48:49]
	v_cvt_pk_bf16_f32 v50, v52, v53
	v_lshl_add_u64 v[48:49], v[192:193], 1, v[48:49]
	global_store_dwordx2 v[48:49], v[50:51], off offset:8
.LBB0_1195:
	s_or_b64 exec, exec, s[0:1]
	v_mov_b32_e32 v201, v200
	v_mov_b32_e32 v48, v200
	v_mov_b32_e32 v49, v200
	v_pk_mul_f32 v[30:31], v[30:31], v[48:49]
	v_pk_mul_f32 v[28:29], v[28:29], v[200:201]
	v_pk_mul_f32 v[26:27], v[26:27], v[48:49]
	v_pk_mul_f32 v[24:25], v[24:25], v[200:201]
	v_mov_b32_dpp v52, v36 row_shl:15 row_mask:0xf bank_mask:0xf bound_ctrl:1
	v_mov_b32_dpp v36, v36 row_shl:14 row_mask:0xf bank_mask:0xf bound_ctrl:1
	v_mov_b32_dpp v104, v32 row_shl:15 row_mask:0xf bank_mask:0xf bound_ctrl:1
	v_mov_b32_dpp v100, v32 row_shl:14 row_mask:0xf bank_mask:0xf bound_ctrl:1
	v_mov_b32_dpp v53, v37 row_shl:15 row_mask:0xf bank_mask:0xf bound_ctrl:1
	v_mov_b32_dpp v37, v37 row_shl:14 row_mask:0xf bank_mask:0xf bound_ctrl:1
	v_mov_b32_dpp v105, v33 row_shl:15 row_mask:0xf bank_mask:0xf bound_ctrl:1
	v_mov_b32_dpp v101, v33 row_shl:14 row_mask:0xf bank_mask:0xf bound_ctrl:1
	v_mov_b32_dpp v96, v38 row_shl:15 row_mask:0xf bank_mask:0xf bound_ctrl:1
	v_mov_b32_dpp v38, v38 row_shl:14 row_mask:0xf bank_mask:0xf bound_ctrl:1
	v_mov_b32_dpp v110, v34 row_shl:15 row_mask:0xf bank_mask:0xf bound_ctrl:1
	v_mov_b32_dpp v34, v34 row_shl:14 row_mask:0xf bank_mask:0xf bound_ctrl:1
	v_mov_b32_dpp v97, v39 row_shl:15 row_mask:0xf bank_mask:0xf bound_ctrl:1
	v_mov_b32_dpp v39, v39 row_shl:14 row_mask:0xf bank_mask:0xf bound_ctrl:1
	v_mov_b32_dpp v111, v35 row_shl:15 row_mask:0xf bank_mask:0xf bound_ctrl:1
	v_mov_b32_dpp v35, v35 row_shl:14 row_mask:0xf bank_mask:0xf bound_ctrl:1
	v_add_f32_dpp v50, v28, v52 row_shr:1 row_mask:0xf bank_mask:0xf bound_ctrl:1
	v_add_f32_dpp v36, v28, v36 row_shr:2 row_mask:0xf bank_mask:0xf bound_ctrl:1
	v_add_f32_dpp v102, v24, v104 row_shr:1 row_mask:0xf bank_mask:0xf bound_ctrl:1
	v_add_f32_dpp v98, v24, v100 row_shr:2 row_mask:0xf bank_mask:0xf bound_ctrl:1
	v_add_f32_dpp v51, v29, v53 row_shr:1 row_mask:0xf bank_mask:0xf bound_ctrl:1
	v_add_f32_dpp v37, v29, v37 row_shr:2 row_mask:0xf bank_mask:0xf bound_ctrl:1
	v_add_f32_dpp v103, v25, v105 row_shr:1 row_mask:0xf bank_mask:0xf bound_ctrl:1
	v_add_f32_dpp v99, v25, v101 row_shr:2 row_mask:0xf bank_mask:0xf bound_ctrl:1
	v_add_f32_dpp v54, v30, v96 row_shr:1 row_mask:0xf bank_mask:0xf bound_ctrl:1
	v_add_f32_dpp v32, v30, v38 row_shr:2 row_mask:0xf bank_mask:0xf bound_ctrl:1
	v_add_f32_dpp v108, v26, v110 row_shr:1 row_mask:0xf bank_mask:0xf bound_ctrl:1
	v_add_f32_dpp v34, v26, v34 row_shr:2 row_mask:0xf bank_mask:0xf bound_ctrl:1
	v_add_f32_dpp v55, v31, v97 row_shr:1 row_mask:0xf bank_mask:0xf bound_ctrl:1
	v_add_f32_dpp v33, v31, v39 row_shr:2 row_mask:0xf bank_mask:0xf bound_ctrl:1
	v_add_f32_dpp v109, v27, v111 row_shr:1 row_mask:0xf bank_mask:0xf bound_ctrl:1
	v_add_f32_dpp v35, v27, v35 row_shr:2 row_mask:0xf bank_mask:0xf bound_ctrl:1
	s_and_saveexec_b64 s[0:1], s[14:15]
	s_cbranch_execz .LBB0_1197
	v_pk_fma_f32 v[32:33], v[70:71], v[32:33], v[82:83]
	v_pk_fma_f32 v[32:33], v[66:67], v[54:55], v[32:33]
	v_pk_fma_f32 v[36:37], v[68:69], v[36:37], v[80:81]
	v_pk_fma_f32 v[32:33], v[30:31], v[62:63], v[32:33]
	v_pk_fma_f32 v[36:37], v[64:65], v[50:51], v[36:37]
	v_mul_f32_e32 v48, 0xbfb8aa3b, v32
	v_mul_f32_e32 v49, 0xbfb8aa3b, v33
	v_pk_fma_f32 v[36:37], v[28:29], v[60:61], v[36:37]
	v_exp_f32_e32 v48, v48
	v_exp_f32_e32 v49, v49
	v_mul_f32_e32 v38, 0xbfb8aa3b, v36
	v_mul_f32_e32 v39, 0xbfb8aa3b, v37
	v_exp_f32_e32 v38, v38
	v_exp_f32_e32 v39, v39
	v_add_f32_e32 v48, 1.0, v48
	v_add_f32_e32 v49, 1.0, v49
	v_rcp_f32_e32 v48, v48
	v_rcp_f32_e32 v49, v49
	v_add_f32_e32 v38, 1.0, v38
	v_add_f32_e32 v39, 1.0, v39
	v_pk_fma_f32 v[34:35], v[90:91], v[34:35], v[94:95]
	v_rcp_f32_e32 v38, v38
	v_rcp_f32_e32 v39, v39
	v_pk_fma_f32 v[34:35], v[86:87], v[108:109], v[34:35]
	v_pk_fma_f32 v[98:99], v[88:89], v[98:99], v[92:93]
	v_pk_fma_f32 v[34:35], v[26:27], v[58:59], v[34:35]
	v_pk_mul_f32 v[32:33], v[32:33], v[48:49]
	v_pk_fma_f32 v[98:99], v[84:85], v[102:103], v[98:99]
	v_pk_mul_f32 v[32:33], v[34:35], v[32:33]
	v_pk_fma_f32 v[50:51], v[24:25], v[56:57], v[98:99]
	v_pk_mul_f32 v[36:37], v[36:37], v[38:39]
	v_cvt_pk_bf16_f32 v35, v32, v33
	v_mov_b64_e32 v[32:33], s[34:35]
	v_pk_mul_f32 v[36:37], v[50:51], v[36:37]
	v_mad_i64_i32 v[32:33], s[12:13], v197, s92, v[32:33]
	v_cvt_pk_bf16_f32 v34, v36, v37
	v_lshl_add_u64 v[32:33], v[192:193], 1, v[32:33]
	global_store_dwordx2 v[32:33], v[34:35], off offset:8
.LBB0_1197:
	s_or_b64 exec, exec, s[0:1]
	v_mov_b32_dpp v36, v28 row_shl:15 row_mask:0xf bank_mask:0xf bound_ctrl:1
	v_mov_b32_dpp v28, v28 row_shl:14 row_mask:0xf bank_mask:0xf bound_ctrl:1
	v_mov_b32_dpp v96, v24 row_shl:15 row_mask:0xf bank_mask:0xf bound_ctrl:1
	v_mov_b32_dpp v52, v24 row_shl:14 row_mask:0xf bank_mask:0xf bound_ctrl:1
	v_mov_b32_dpp v37, v29 row_shl:15 row_mask:0xf bank_mask:0xf bound_ctrl:1
	v_mov_b32_dpp v29, v29 row_shl:14 row_mask:0xf bank_mask:0xf bound_ctrl:1
	v_mov_b32_dpp v97, v25 row_shl:15 row_mask:0xf bank_mask:0xf bound_ctrl:1
	v_mov_b32_dpp v53, v25 row_shl:14 row_mask:0xf bank_mask:0xf bound_ctrl:1
	v_mov_b32_dpp v48, v30 row_shl:15 row_mask:0xf bank_mask:0xf bound_ctrl:1
	v_mov_b32_dpp v30, v30 row_shl:14 row_mask:0xf bank_mask:0xf bound_ctrl:1
	v_mov_b32_dpp v102, v26 row_shl:15 row_mask:0xf bank_mask:0xf bound_ctrl:1
	v_mov_b32_dpp v26, v26 row_shl:14 row_mask:0xf bank_mask:0xf bound_ctrl:1
	v_mov_b32_dpp v49, v31 row_shl:15 row_mask:0xf bank_mask:0xf bound_ctrl:1
	v_mov_b32_dpp v31, v31 row_shl:14 row_mask:0xf bank_mask:0xf bound_ctrl:1
	v_mov_b32_dpp v103, v27 row_shl:15 row_mask:0xf bank_mask:0xf bound_ctrl:1
	v_mov_b32_dpp v27, v27 row_shl:14 row_mask:0xf bank_mask:0xf bound_ctrl:1
	v_add_f32_dpp v34, v76, v36 row_shr:1 row_mask:0xf bank_mask:0xf bound_ctrl:1
	v_add_f32_dpp v28, v76, v28 row_shr:2 row_mask:0xf bank_mask:0xf bound_ctrl:1
	v_add_f32_dpp v54, v72, v96 row_shr:1 row_mask:0xf bank_mask:0xf bound_ctrl:1
	v_add_f32_dpp v50, v72, v52 row_shr:2 row_mask:0xf bank_mask:0xf bound_ctrl:1
	v_add_f32_dpp v35, v77, v37 row_shr:1 row_mask:0xf bank_mask:0xf bound_ctrl:1
	v_add_f32_dpp v29, v77, v29 row_shr:2 row_mask:0xf bank_mask:0xf bound_ctrl:1
	v_add_f32_dpp v55, v73, v97 row_shr:1 row_mask:0xf bank_mask:0xf bound_ctrl:1
	v_add_f32_dpp v51, v73, v53 row_shr:2 row_mask:0xf bank_mask:0xf bound_ctrl:1
	v_add_f32_dpp v38, v78, v48 row_shr:1 row_mask:0xf bank_mask:0xf bound_ctrl:1
	v_add_f32_dpp v24, v78, v30 row_shr:2 row_mask:0xf bank_mask:0xf bound_ctrl:1
	v_add_f32_dpp v100, v74, v102 row_shr:1 row_mask:0xf bank_mask:0xf bound_ctrl:1
	v_add_f32_dpp v26, v74, v26 row_shr:2 row_mask:0xf bank_mask:0xf bound_ctrl:1
	v_add_f32_dpp v39, v79, v49 row_shr:1 row_mask:0xf bank_mask:0xf bound_ctrl:1
	v_add_f32_dpp v25, v79, v31 row_shr:2 row_mask:0xf bank_mask:0xf bound_ctrl:1
	v_add_f32_dpp v101, v75, v103 row_shr:1 row_mask:0xf bank_mask:0xf bound_ctrl:1
	v_add_f32_dpp v27, v75, v27 row_shr:2 row_mask:0xf bank_mask:0xf bound_ctrl:1
	s_and_saveexec_b64 s[0:1], s[22:23]
	s_cbranch_execz .LBB0_1199
	v_pk_fma_f32 v[24:25], v[70:71], v[24:25], v[82:83]
	v_pk_fma_f32 v[24:25], v[66:67], v[38:39], v[24:25]
	v_pk_fma_f32 v[28:29], v[68:69], v[28:29], v[80:81]
	v_pk_fma_f32 v[24:25], v[78:79], v[62:63], v[24:25]
	v_pk_fma_f32 v[28:29], v[64:65], v[34:35], v[28:29]
	v_mul_f32_e32 v32, 0xbfb8aa3b, v24
	v_mul_f32_e32 v33, 0xbfb8aa3b, v25
	v_pk_fma_f32 v[28:29], v[76:77], v[60:61], v[28:29]
	v_exp_f32_e32 v32, v32
	v_exp_f32_e32 v33, v33
	v_mul_f32_e32 v30, 0xbfb8aa3b, v28
	v_mul_f32_e32 v31, 0xbfb8aa3b, v29
	v_exp_f32_e32 v30, v30
	v_exp_f32_e32 v31, v31
	v_add_f32_e32 v32, 1.0, v32
	v_add_f32_e32 v33, 1.0, v33
	v_rcp_f32_e32 v32, v32
	v_rcp_f32_e32 v33, v33
	v_add_f32_e32 v30, 1.0, v30
	v_add_f32_e32 v31, 1.0, v31
	v_pk_fma_f32 v[26:27], v[90:91], v[26:27], v[94:95]
	v_rcp_f32_e32 v30, v30
	v_rcp_f32_e32 v31, v31
	v_pk_fma_f32 v[26:27], v[86:87], v[100:101], v[26:27]
	v_pk_fma_f32 v[50:51], v[88:89], v[50:51], v[92:93]
	v_pk_fma_f32 v[26:27], v[74:75], v[58:59], v[26:27]
	v_pk_mul_f32 v[24:25], v[24:25], v[32:33]
	v_pk_fma_f32 v[50:51], v[84:85], v[54:55], v[50:51]
	v_pk_mul_f32 v[24:25], v[26:27], v[24:25]
	v_pk_fma_f32 v[34:35], v[72:73], v[56:57], v[50:51]
	v_pk_mul_f32 v[28:29], v[28:29], v[30:31]
	v_cvt_pk_bf16_f32 v27, v24, v25
	v_mov_b64_e32 v[24:25], s[34:35]
	v_pk_mul_f32 v[28:29], v[34:35], v[28:29]
	v_mad_i64_i32 v[24:25], s[12:13], v168, s92, v[24:25]
	v_cvt_pk_bf16_f32 v26, v28, v29
	v_lshl_add_u64 v[24:25], v[192:193], 1, v[24:25]
	global_store_dwordx2 v[24:25], v[26:27], off offset:8

.LBB0_1207:
	s_or_b64 exec, exec, s[0:1]
	v_mov_b32_e32 v197, v196
	v_mov_b32_e32 v24, v196
	v_mov_b32_e32 v25, v196
	v_pk_mul_f32 v[14:15], v[14:15], v[24:25]
	v_pk_mul_f32 v[12:13], v[12:13], v[196:197]
	v_pk_mul_f32 v[10:11], v[10:11], v[24:25]
	v_pk_mul_f32 v[8:9], v[8:9], v[196:197]
	v_mov_b32_dpp v28, v20 row_shl:15 row_mask:0xf bank_mask:0xf bound_ctrl:1
	v_mov_b32_dpp v20, v20 row_shl:14 row_mask:0xf bank_mask:0xf bound_ctrl:1
	v_mov_b32_dpp v48, v16 row_shl:15 row_mask:0xf bank_mask:0xf bound_ctrl:1
	v_mov_b32_dpp v36, v16 row_shl:14 row_mask:0xf bank_mask:0xf bound_ctrl:1
	v_mov_b32_dpp v29, v21 row_shl:15 row_mask:0xf bank_mask:0xf bound_ctrl:1
	v_mov_b32_dpp v21, v21 row_shl:14 row_mask:0xf bank_mask:0xf bound_ctrl:1
	v_mov_b32_dpp v49, v17 row_shl:15 row_mask:0xf bank_mask:0xf bound_ctrl:1
	v_mov_b32_dpp v37, v17 row_shl:14 row_mask:0xf bank_mask:0xf bound_ctrl:1
	v_mov_b32_dpp v32, v22 row_shl:15 row_mask:0xf bank_mask:0xf bound_ctrl:1
	v_mov_b32_dpp v22, v22 row_shl:14 row_mask:0xf bank_mask:0xf bound_ctrl:1
	v_mov_b32_dpp v54, v18 row_shl:15 row_mask:0xf bank_mask:0xf bound_ctrl:1
	v_mov_b32_dpp v18, v18 row_shl:14 row_mask:0xf bank_mask:0xf bound_ctrl:1
	v_mov_b32_dpp v33, v23 row_shl:15 row_mask:0xf bank_mask:0xf bound_ctrl:1
	v_mov_b32_dpp v23, v23 row_shl:14 row_mask:0xf bank_mask:0xf bound_ctrl:1
	v_mov_b32_dpp v55, v19 row_shl:15 row_mask:0xf bank_mask:0xf bound_ctrl:1
	v_mov_b32_dpp v19, v19 row_shl:14 row_mask:0xf bank_mask:0xf bound_ctrl:1
	v_add_f32_dpp v26, v12, v28 row_shr:1 row_mask:0xf bank_mask:0xf bound_ctrl:1
	v_add_f32_dpp v20, v12, v20 row_shr:2 row_mask:0xf bank_mask:0xf bound_ctrl:1
	v_add_f32_dpp v38, v8, v48 row_shr:1 row_mask:0xf bank_mask:0xf bound_ctrl:1
	v_add_f32_dpp v34, v8, v36 row_shr:2 row_mask:0xf bank_mask:0xf bound_ctrl:1
	v_add_f32_dpp v27, v13, v29 row_shr:1 row_mask:0xf bank_mask:0xf bound_ctrl:1
	v_add_f32_dpp v21, v13, v21 row_shr:2 row_mask:0xf bank_mask:0xf bound_ctrl:1
	v_add_f32_dpp v39, v9, v49 row_shr:1 row_mask:0xf bank_mask:0xf bound_ctrl:1
	v_add_f32_dpp v35, v9, v37 row_shr:2 row_mask:0xf bank_mask:0xf bound_ctrl:1
	v_add_f32_dpp v30, v14, v32 row_shr:1 row_mask:0xf bank_mask:0xf bound_ctrl:1
	v_add_f32_dpp v16, v14, v22 row_shr:2 row_mask:0xf bank_mask:0xf bound_ctrl:1
	v_add_f32_dpp v52, v10, v54 row_shr:1 row_mask:0xf bank_mask:0xf bound_ctrl:1
	v_add_f32_dpp v18, v10, v18 row_shr:2 row_mask:0xf bank_mask:0xf bound_ctrl:1
	v_add_f32_dpp v31, v15, v33 row_shr:1 row_mask:0xf bank_mask:0xf bound_ctrl:1
	v_add_f32_dpp v17, v15, v23 row_shr:2 row_mask:0xf bank_mask:0xf bound_ctrl:1
	v_add_f32_dpp v53, v11, v55 row_shr:1 row_mask:0xf bank_mask:0xf bound_ctrl:1
	v_add_f32_dpp v19, v11, v19 row_shr:2 row_mask:0xf bank_mask:0xf bound_ctrl:1
	s_and_saveexec_b64 s[0:1], s[18:19]
	s_cbranch_execz .LBB0_1209
	v_pk_fma_f32 v[16:17], v[70:71], v[16:17], v[82:83]
	v_pk_fma_f32 v[16:17], v[66:67], v[30:31], v[16:17]
	v_pk_fma_f32 v[20:21], v[68:69], v[20:21], v[80:81]
	v_pk_fma_f32 v[16:17], v[14:15], v[62:63], v[16:17]
	v_pk_fma_f32 v[20:21], v[64:65], v[26:27], v[20:21]
	v_mul_f32_e32 v24, 0xbfb8aa3b, v16
	v_mul_f32_e32 v25, 0xbfb8aa3b, v17
	v_pk_fma_f32 v[20:21], v[12:13], v[60:61], v[20:21]
	v_exp_f32_e32 v24, v24
	v_exp_f32_e32 v25, v25
	v_mul_f32_e32 v22, 0xbfb8aa3b, v20
	v_mul_f32_e32 v23, 0xbfb8aa3b, v21
	v_exp_f32_e32 v22, v22
	v_exp_f32_e32 v23, v23
	v_add_f32_e32 v24, 1.0, v24
	v_add_f32_e32 v25, 1.0, v25
	v_rcp_f32_e32 v24, v24
	v_rcp_f32_e32 v25, v25
	v_add_f32_e32 v22, 1.0, v22
	v_add_f32_e32 v23, 1.0, v23
	v_pk_fma_f32 v[18:19], v[90:91], v[18:19], v[94:95]
	v_rcp_f32_e32 v22, v22
	v_rcp_f32_e32 v23, v23
	v_pk_fma_f32 v[18:19], v[86:87], v[52:53], v[18:19]
	v_pk_fma_f32 v[34:35], v[88:89], v[34:35], v[92:93]
	v_pk_fma_f32 v[18:19], v[10:11], v[58:59], v[18:19]
	v_pk_mul_f32 v[16:17], v[16:17], v[24:25]
	v_pk_fma_f32 v[34:35], v[84:85], v[38:39], v[34:35]
	v_pk_mul_f32 v[16:17], v[18:19], v[16:17]
	v_pk_fma_f32 v[26:27], v[8:9], v[56:57], v[34:35]
	v_pk_mul_f32 v[20:21], v[20:21], v[22:23]
	v_cvt_pk_bf16_f32 v19, v16, v17
	v_mov_b64_e32 v[16:17], s[34:35]
	v_pk_mul_f32 v[20:21], v[26:27], v[20:21]
	v_mad_i64_i32 v[16:17], s[12:13], v152, s92, v[16:17]
	v_cvt_pk_bf16_f32 v18, v20, v21
	v_lshl_add_u64 v[16:17], v[192:193], 1, v[16:17]
	global_store_dwordx2 v[16:17], v[18:19], off offset:8
.LBB0_1209:
	s_or_b64 exec, exec, s[0:1]
	v_mov_b32_e32 v195, v194
	v_mov_b32_e32 v16, v194
	v_mov_b32_e32 v17, v194
	v_pk_mul_f32 v[6:7], v[6:7], v[16:17]
	v_pk_mul_f32 v[4:5], v[4:5], v[194:195]
	v_pk_mul_f32 v[2:3], v[2:3], v[16:17]
	v_pk_mul_f32 v[0:1], v[0:1], v[194:195]
	v_mov_b32_dpp v20, v12 row_shl:15 row_mask:0xf bank_mask:0xf bound_ctrl:1
	v_mov_b32_dpp v12, v12 row_shl:14 row_mask:0xf bank_mask:0xf bound_ctrl:1
	v_mov_b32_dpp v32, v8 row_shl:15 row_mask:0xf bank_mask:0xf bound_ctrl:1
	v_mov_b32_dpp v28, v8 row_shl:14 row_mask:0xf bank_mask:0xf bound_ctrl:1
	v_mov_b32_dpp v21, v13 row_shl:15 row_mask:0xf bank_mask:0xf bound_ctrl:1
	v_mov_b32_dpp v13, v13 row_shl:14 row_mask:0xf bank_mask:0xf bound_ctrl:1
	v_mov_b32_dpp v33, v9 row_shl:15 row_mask:0xf bank_mask:0xf bound_ctrl:1
	v_mov_b32_dpp v29, v9 row_shl:14 row_mask:0xf bank_mask:0xf bound_ctrl:1
	v_mov_b32_dpp v24, v14 row_shl:15 row_mask:0xf bank_mask:0xf bound_ctrl:1
	v_mov_b32_dpp v14, v14 row_shl:14 row_mask:0xf bank_mask:0xf bound_ctrl:1
	v_mov_b32_dpp v38, v10 row_shl:15 row_mask:0xf bank_mask:0xf bound_ctrl:1
	v_mov_b32_dpp v10, v10 row_shl:14 row_mask:0xf bank_mask:0xf bound_ctrl:1
	v_mov_b32_dpp v25, v15 row_shl:15 row_mask:0xf bank_mask:0xf bound_ctrl:1
	v_mov_b32_dpp v15, v15 row_shl:14 row_mask:0xf bank_mask:0xf bound_ctrl:1
	v_mov_b32_dpp v39, v11 row_shl:15 row_mask:0xf bank_mask:0xf bound_ctrl:1
	v_mov_b32_dpp v11, v11 row_shl:14 row_mask:0xf bank_mask:0xf bound_ctrl:1
	v_add_f32_dpp v18, v4, v20 row_shr:1 row_mask:0xf bank_mask:0xf bound_ctrl:1
	v_add_f32_dpp v12, v4, v12 row_shr:2 row_mask:0xf bank_mask:0xf bound_ctrl:1
	v_add_f32_dpp v30, v0, v32 row_shr:1 row_mask:0xf bank_mask:0xf bound_ctrl:1
	v_add_f32_dpp v26, v0, v28 row_shr:2 row_mask:0xf bank_mask:0xf bound_ctrl:1
	v_add_f32_dpp v19, v5, v21 row_shr:1 row_mask:0xf bank_mask:0xf bound_ctrl:1
	v_add_f32_dpp v13, v5, v13 row_shr:2 row_mask:0xf bank_mask:0xf bound_ctrl:1
	v_add_f32_dpp v31, v1, v33 row_shr:1 row_mask:0xf bank_mask:0xf bound_ctrl:1
	v_add_f32_dpp v27, v1, v29 row_shr:2 row_mask:0xf bank_mask:0xf bound_ctrl:1
	v_add_f32_dpp v22, v6, v24 row_shr:1 row_mask:0xf bank_mask:0xf bound_ctrl:1
	v_add_f32_dpp v8, v6, v14 row_shr:2 row_mask:0xf bank_mask:0xf bound_ctrl:1
	v_add_f32_dpp v36, v2, v38 row_shr:1 row_mask:0xf bank_mask:0xf bound_ctrl:1
	v_add_f32_dpp v10, v2, v10 row_shr:2 row_mask:0xf bank_mask:0xf bound_ctrl:1
	v_add_f32_dpp v23, v7, v25 row_shr:1 row_mask:0xf bank_mask:0xf bound_ctrl:1
	v_add_f32_dpp v9, v7, v15 row_shr:2 row_mask:0xf bank_mask:0xf bound_ctrl:1
	v_add_f32_dpp v37, v3, v39 row_shr:1 row_mask:0xf bank_mask:0xf bound_ctrl:1
	v_add_f32_dpp v11, v3, v11 row_shr:2 row_mask:0xf bank_mask:0xf bound_ctrl:1
	s_and_saveexec_b64 s[0:1], s[16:17]
	s_cbranch_execz .LBB0_1211
	v_pk_fma_f32 v[8:9], v[70:71], v[8:9], v[82:83]
	v_pk_fma_f32 v[8:9], v[66:67], v[22:23], v[8:9]
	v_pk_fma_f32 v[12:13], v[68:69], v[12:13], v[80:81]
	v_pk_fma_f32 v[8:9], v[6:7], v[62:63], v[8:9]
	v_pk_fma_f32 v[12:13], v[64:65], v[18:19], v[12:13]
	v_mul_f32_e32 v16, 0xbfb8aa3b, v8
	v_mul_f32_e32 v17, 0xbfb8aa3b, v9
	v_pk_fma_f32 v[12:13], v[4:5], v[60:61], v[12:13]
	v_exp_f32_e32 v16, v16
	v_exp_f32_e32 v17, v17
	v_mul_f32_e32 v14, 0xbfb8aa3b, v12
	v_mul_f32_e32 v15, 0xbfb8aa3b, v13
	v_exp_f32_e32 v14, v14
	v_exp_f32_e32 v15, v15
	v_add_f32_e32 v16, 1.0, v16
	v_add_f32_e32 v17, 1.0, v17
	v_rcp_f32_e32 v16, v16
	v_rcp_f32_e32 v17, v17
	v_add_f32_e32 v14, 1.0, v14
	v_add_f32_e32 v15, 1.0, v15
	v_pk_fma_f32 v[10:11], v[90:91], v[10:11], v[94:95]
	v_rcp_f32_e32 v14, v14
	v_rcp_f32_e32 v15, v15
	v_pk_fma_f32 v[10:11], v[86:87], v[36:37], v[10:11]
	v_pk_fma_f32 v[26:27], v[88:89], v[26:27], v[92:93]
	v_pk_fma_f32 v[10:11], v[2:3], v[58:59], v[10:11]
	v_pk_mul_f32 v[8:9], v[8:9], v[16:17]
	v_pk_fma_f32 v[26:27], v[84:85], v[30:31], v[26:27]
	v_pk_mul_f32 v[8:9], v[10:11], v[8:9]
	v_pk_fma_f32 v[18:19], v[0:1], v[56:57], v[26:27]
	v_pk_mul_f32 v[12:13], v[12:13], v[14:15]
	v_cvt_pk_bf16_f32 v11, v8, v9
	v_mov_b64_e32 v[8:9], s[34:35]
	v_pk_mul_f32 v[12:13], v[18:19], v[12:13]
	v_mad_i64_i32 v[8:9], s[12:13], v132, s92, v[8:9]
	v_cvt_pk_bf16_f32 v10, v12, v13
	v_lshl_add_u64 v[8:9], v[192:193], 1, v[8:9]
	global_store_dwordx2 v[8:9], v[10:11], off offset:8
.LBB0_1211:
	s_or_b64 exec, exec, s[0:1]
	v_mov_b32_dpp v12, v4 row_shl:15 row_mask:0xf bank_mask:0xf bound_ctrl:1
	v_mov_b32_dpp v4, v4 row_shl:14 row_mask:0xf bank_mask:0xf bound_ctrl:1
	v_mov_b32_dpp v24, v0 row_shl:15 row_mask:0xf bank_mask:0xf bound_ctrl:1
	v_mov_b32_dpp v20, v0 row_shl:14 row_mask:0xf bank_mask:0xf bound_ctrl:1
	v_mov_b32_dpp v13, v5 row_shl:15 row_mask:0xf bank_mask:0xf bound_ctrl:1
	v_mov_b32_dpp v5, v5 row_shl:14 row_mask:0xf bank_mask:0xf bound_ctrl:1
	v_mov_b32_dpp v25, v1 row_shl:15 row_mask:0xf bank_mask:0xf bound_ctrl:1
	v_mov_b32_dpp v21, v1 row_shl:14 row_mask:0xf bank_mask:0xf bound_ctrl:1
	v_mov_b32_dpp v16, v6 row_shl:15 row_mask:0xf bank_mask:0xf bound_ctrl:1
	v_mov_b32_dpp v6, v6 row_shl:14 row_mask:0xf bank_mask:0xf bound_ctrl:1
	v_mov_b32_dpp v30, v2 row_shl:15 row_mask:0xf bank_mask:0xf bound_ctrl:1
	v_mov_b32_dpp v2, v2 row_shl:14 row_mask:0xf bank_mask:0xf bound_ctrl:1
	v_mov_b32_dpp v17, v7 row_shl:15 row_mask:0xf bank_mask:0xf bound_ctrl:1
	v_mov_b32_dpp v7, v7 row_shl:14 row_mask:0xf bank_mask:0xf bound_ctrl:1
	v_mov_b32_dpp v31, v3 row_shl:15 row_mask:0xf bank_mask:0xf bound_ctrl:1
	v_mov_b32_dpp v3, v3 row_shl:14 row_mask:0xf bank_mask:0xf bound_ctrl:1
	v_add_f32_dpp v10, v44, v12 row_shr:1 row_mask:0xf bank_mask:0xf bound_ctrl:1
	v_add_f32_dpp v4, v44, v4 row_shr:2 row_mask:0xf bank_mask:0xf bound_ctrl:1
	v_add_f32_dpp v22, v40, v24 row_shr:1 row_mask:0xf bank_mask:0xf bound_ctrl:1
	v_add_f32_dpp v18, v40, v20 row_shr:2 row_mask:0xf bank_mask:0xf bound_ctrl:1
	v_add_f32_dpp v11, v45, v13 row_shr:1 row_mask:0xf bank_mask:0xf bound_ctrl:1
	v_add_f32_dpp v5, v45, v5 row_shr:2 row_mask:0xf bank_mask:0xf bound_ctrl:1
	v_add_f32_dpp v23, v41, v25 row_shr:1 row_mask:0xf bank_mask:0xf bound_ctrl:1
	v_add_f32_dpp v19, v41, v21 row_shr:2 row_mask:0xf bank_mask:0xf bound_ctrl:1
	v_add_f32_dpp v14, v46, v16 row_shr:1 row_mask:0xf bank_mask:0xf bound_ctrl:1
	v_add_f32_dpp v0, v46, v6 row_shr:2 row_mask:0xf bank_mask:0xf bound_ctrl:1
	v_add_f32_dpp v28, v42, v30 row_shr:1 row_mask:0xf bank_mask:0xf bound_ctrl:1
	v_add_f32_dpp v2, v42, v2 row_shr:2 row_mask:0xf bank_mask:0xf bound_ctrl:1
	v_add_f32_dpp v15, v47, v17 row_shr:1 row_mask:0xf bank_mask:0xf bound_ctrl:1
	v_add_f32_dpp v1, v47, v7 row_shr:2 row_mask:0xf bank_mask:0xf bound_ctrl:1
	v_add_f32_dpp v29, v43, v31 row_shr:1 row_mask:0xf bank_mask:0xf bound_ctrl:1
	v_add_f32_dpp v3, v43, v3 row_shr:2 row_mask:0xf bank_mask:0xf bound_ctrl:1
	s_and_saveexec_b64 s[0:1], s[26:27]
	s_cbranch_execz .LBB0_1213
	v_pk_fma_f32 v[0:1], v[70:71], v[0:1], v[82:83]
	v_pk_fma_f32 v[0:1], v[66:67], v[14:15], v[0:1]
	v_pk_fma_f32 v[4:5], v[68:69], v[4:5], v[80:81]
	v_pk_fma_f32 v[0:1], v[46:47], v[62:63], v[0:1]
	v_pk_fma_f32 v[4:5], v[64:65], v[10:11], v[4:5]
	v_mul_f32_e32 v8, 0xbfb8aa3b, v0
	v_mul_f32_e32 v9, 0xbfb8aa3b, v1
	v_pk_fma_f32 v[4:5], v[44:45], v[60:61], v[4:5]
	v_exp_f32_e32 v8, v8
	v_exp_f32_e32 v9, v9
	v_mul_f32_e32 v6, 0xbfb8aa3b, v4
	v_mul_f32_e32 v7, 0xbfb8aa3b, v5
	v_exp_f32_e32 v6, v6
	v_exp_f32_e32 v7, v7
	v_add_f32_e32 v8, 1.0, v8
	v_add_f32_e32 v9, 1.0, v9
	v_rcp_f32_e32 v8, v8
	v_rcp_f32_e32 v9, v9
	v_add_f32_e32 v6, 1.0, v6
	v_add_f32_e32 v7, 1.0, v7
	v_pk_fma_f32 v[2:3], v[90:91], v[2:3], v[94:95]
	v_rcp_f32_e32 v6, v6
	v_rcp_f32_e32 v7, v7
	v_pk_fma_f32 v[2:3], v[86:87], v[28:29], v[2:3]
	v_pk_fma_f32 v[18:19], v[88:89], v[18:19], v[92:93]
	v_pk_fma_f32 v[2:3], v[42:43], v[58:59], v[2:3]
	v_pk_mul_f32 v[0:1], v[0:1], v[8:9]
	v_pk_fma_f32 v[18:19], v[84:85], v[22:23], v[18:19]
	v_pk_mul_f32 v[0:1], v[2:3], v[0:1]
	v_pk_fma_f32 v[10:11], v[40:41], v[56:57], v[18:19]
	v_pk_mul_f32 v[4:5], v[4:5], v[6:7]
	v_cvt_pk_bf16_f32 v3, v0, v1
	v_mov_b64_e32 v[0:1], s[34:35]
	v_pk_mul_f32 v[4:5], v[10:11], v[4:5]
	v_mad_i64_i32 v[0:1], s[12:13], v133, s92, v[0:1]
	v_cvt_pk_bf16_f32 v2, v4, v5
	v_lshl_add_u64 v[0:1], v[192:193], 1, v[0:1]
	global_store_dwordx2 v[0:1], v[2:3], off offset:8

.LBB0_2266:
	s_or_b64 exec, exec, s[12:13]
	v_pk_mul_f32 v[110:111], v[110:111], v[200:201] op_sel_hi:[1,0]
	v_pk_mul_f32 v[108:109], v[108:109], v[200:201] op_sel_hi:[1,0]
	v_pk_mul_f32 v[106:107], v[106:107], v[200:201] op_sel_hi:[1,0]
	v_pk_mul_f32 v[104:105], v[104:105], v[200:201] op_sel_hi:[1,0]
	v_add_u32_e32 v195, s18, v225
	s_waitcnt lgkmcnt(0)
	v_mov_b32_dpp v164, v148 row_shl:15 row_mask:0xf bank_mask:0xf bound_ctrl:1
	v_mov_b32_dpp v148, v148 row_shl:14 row_mask:0xf bank_mask:0xf bound_ctrl:1
	v_mov_b32_dpp v204, v144 row_shl:15 row_mask:0xf bank_mask:0xf bound_ctrl:1
	v_mov_b32_dpp v172, v144 row_shl:14 row_mask:0xf bank_mask:0xf bound_ctrl:1
	v_mov_b32_dpp v165, v149 row_shl:15 row_mask:0xf bank_mask:0xf bound_ctrl:1
	v_mov_b32_dpp v149, v149 row_shl:14 row_mask:0xf bank_mask:0xf bound_ctrl:1
	v_mov_b32_dpp v205, v145 row_shl:15 row_mask:0xf bank_mask:0xf bound_ctrl:1
	v_mov_b32_dpp v173, v145 row_shl:14 row_mask:0xf bank_mask:0xf bound_ctrl:1
	v_mov_b32_dpp v168, v150 row_shl:15 row_mask:0xf bank_mask:0xf bound_ctrl:1
	v_mov_b32_dpp v150, v150 row_shl:14 row_mask:0xf bank_mask:0xf bound_ctrl:1
	v_mov_b32_dpp v210, v146 row_shl:15 row_mask:0xf bank_mask:0xf bound_ctrl:1
	v_mov_b32_dpp v146, v146 row_shl:14 row_mask:0xf bank_mask:0xf bound_ctrl:1
	v_mov_b32_dpp v169, v151 row_shl:15 row_mask:0xf bank_mask:0xf bound_ctrl:1
	v_mov_b32_dpp v151, v151 row_shl:14 row_mask:0xf bank_mask:0xf bound_ctrl:1
	v_mov_b32_dpp v211, v147 row_shl:15 row_mask:0xf bank_mask:0xf bound_ctrl:1
	v_mov_b32_dpp v147, v147 row_shl:14 row_mask:0xf bank_mask:0xf bound_ctrl:1
	v_add_f32_dpp v162, v108, v164 row_shr:1 row_mask:0xf bank_mask:0xf bound_ctrl:1
	v_add_f32_dpp v148, v108, v148 row_shr:2 row_mask:0xf bank_mask:0xf bound_ctrl:1
	v_add_f32_dpp v174, v104, v204 row_shr:1 row_mask:0xf bank_mask:0xf bound_ctrl:1
	v_add_f32_dpp v170, v104, v172 row_shr:2 row_mask:0xf bank_mask:0xf bound_ctrl:1
	v_add_f32_dpp v163, v109, v165 row_shr:1 row_mask:0xf bank_mask:0xf bound_ctrl:1
	v_add_f32_dpp v149, v109, v149 row_shr:2 row_mask:0xf bank_mask:0xf bound_ctrl:1
	v_add_f32_dpp v175, v105, v205 row_shr:1 row_mask:0xf bank_mask:0xf bound_ctrl:1
	v_add_f32_dpp v171, v105, v173 row_shr:2 row_mask:0xf bank_mask:0xf bound_ctrl:1
	v_add_f32_dpp v166, v110, v168 row_shr:1 row_mask:0xf bank_mask:0xf bound_ctrl:1
	v_add_f32_dpp v144, v110, v150 row_shr:2 row_mask:0xf bank_mask:0xf bound_ctrl:1
	v_add_f32_dpp v208, v106, v210 row_shr:1 row_mask:0xf bank_mask:0xf bound_ctrl:1
	v_add_f32_dpp v146, v106, v146 row_shr:2 row_mask:0xf bank_mask:0xf bound_ctrl:1
	v_add_f32_dpp v167, v111, v169 row_shr:1 row_mask:0xf bank_mask:0xf bound_ctrl:1
	v_add_f32_dpp v145, v111, v151 row_shr:2 row_mask:0xf bank_mask:0xf bound_ctrl:1
	v_add_f32_dpp v209, v107, v211 row_shr:1 row_mask:0xf bank_mask:0xf bound_ctrl:1
	v_add_f32_dpp v147, v107, v147 row_shr:2 row_mask:0xf bank_mask:0xf bound_ctrl:1
	v_cmp_gt_i32_e64 s[12:13], s79, v195
	v_add_u32_e32 v197, s33, v195
	s_and_saveexec_b64 s[14:15], s[12:13]
	s_cbranch_execz .LBB0_2268
	s_waitcnt vmcnt(0)
	v_pk_fma_f32 v[144:145], v[126:127], v[144:145], v[130:131]
	v_pk_fma_f32 v[144:145], v[122:123], v[166:167], v[144:145]
	v_pk_fma_f32 v[148:149], v[124:125], v[148:149], v[128:129]
	v_pk_fma_f32 v[144:145], v[110:111], v[118:119], v[144:145]
	v_pk_fma_f32 v[148:149], v[120:121], v[162:163], v[148:149]
	v_mul_f32_e32 v160, 0xbfb8aa3b, v144
	v_mul_f32_e32 v161, 0xbfb8aa3b, v145
	v_pk_fma_f32 v[148:149], v[108:109], v[116:117], v[148:149]
	v_exp_f32_e32 v160, v160
	v_exp_f32_e32 v161, v161
	v_mul_f32_e32 v150, 0xbfb8aa3b, v148
	v_mul_f32_e32 v151, 0xbfb8aa3b, v149
	v_exp_f32_e32 v150, v150
	v_exp_f32_e32 v151, v151
	v_add_f32_e32 v160, 1.0, v160
	v_add_f32_e32 v161, 1.0, v161
	v_rcp_f32_e32 v160, v160
	v_rcp_f32_e32 v161, v161
	v_add_f32_e32 v150, 1.0, v150
	v_add_f32_e32 v151, 1.0, v151
	v_pk_fma_f32 v[146:147], v[138:139], v[146:147], v[142:143]
	v_rcp_f32_e32 v150, v150
	v_rcp_f32_e32 v151, v151
	v_pk_fma_f32 v[146:147], v[134:135], v[208:209], v[146:147]
	v_pk_fma_f32 v[170:171], v[136:137], v[170:171], v[140:141]
	v_pk_fma_f32 v[146:147], v[106:107], v[114:115], v[146:147]
	v_pk_mul_f32 v[144:145], v[144:145], v[160:161]
	v_pk_fma_f32 v[170:171], v[132:133], v[174:175], v[170:171]
	v_pk_mul_f32 v[144:145], v[146:147], v[144:145]
	v_pk_fma_f32 v[162:163], v[104:105], v[112:113], v[170:171]
	v_pk_mul_f32 v[148:149], v[148:149], v[150:151]
	v_cvt_pk_bf16_f32 v147, v144, v145
	v_mov_b64_e32 v[144:145], s[36:37]
	v_pk_mul_f32 v[148:149], v[162:163], v[148:149]
	v_mad_i64_i32 v[144:145], s[16:17], v197, s96, v[144:145]
	v_cvt_pk_bf16_f32 v146, v148, v149
	v_lshl_add_u64 v[144:145], v[190:191], 1, v[144:145]
	global_store_dwordx2 v[144:145], v[146:147], off
.LBB0_2268:
	s_or_b64 exec, exec, s[14:15]
	v_pk_mul_f32 v[94:95], v[94:95], v[198:199] op_sel_hi:[1,0]
	v_pk_mul_f32 v[92:93], v[92:93], v[198:199] op_sel_hi:[1,0]
	v_pk_mul_f32 v[90:91], v[90:91], v[198:199] op_sel_hi:[1,0]
	v_pk_mul_f32 v[88:89], v[88:89], v[198:199] op_sel_hi:[1,0]
	v_add_u32_e32 v195, s18, v226
	v_mov_b32_dpp v148, v108 row_shl:15 row_mask:0xf bank_mask:0xf bound_ctrl:1
	v_mov_b32_dpp v108, v108 row_shl:14 row_mask:0xf bank_mask:0xf bound_ctrl:1
	v_mov_b32_dpp v168, v104 row_shl:15 row_mask:0xf bank_mask:0xf bound_ctrl:1
	v_mov_b32_dpp v164, v104 row_shl:14 row_mask:0xf bank_mask:0xf bound_ctrl:1
	v_mov_b32_dpp v149, v109 row_shl:15 row_mask:0xf bank_mask:0xf bound_ctrl:1
	v_mov_b32_dpp v109, v109 row_shl:14 row_mask:0xf bank_mask:0xf bound_ctrl:1
	v_mov_b32_dpp v169, v105 row_shl:15 row_mask:0xf bank_mask:0xf bound_ctrl:1
	v_mov_b32_dpp v165, v105 row_shl:14 row_mask:0xf bank_mask:0xf bound_ctrl:1
	v_mov_b32_dpp v160, v110 row_shl:15 row_mask:0xf bank_mask:0xf bound_ctrl:1
	v_mov_b32_dpp v110, v110 row_shl:14 row_mask:0xf bank_mask:0xf bound_ctrl:1
	v_mov_b32_dpp v174, v106 row_shl:15 row_mask:0xf bank_mask:0xf bound_ctrl:1
	v_mov_b32_dpp v106, v106 row_shl:14 row_mask:0xf bank_mask:0xf bound_ctrl:1
	v_mov_b32_dpp v161, v111 row_shl:15 row_mask:0xf bank_mask:0xf bound_ctrl:1
	v_mov_b32_dpp v111, v111 row_shl:14 row_mask:0xf bank_mask:0xf bound_ctrl:1
	v_mov_b32_dpp v175, v107 row_shl:15 row_mask:0xf bank_mask:0xf bound_ctrl:1
	v_mov_b32_dpp v107, v107 row_shl:14 row_mask:0xf bank_mask:0xf bound_ctrl:1
	v_add_f32_dpp v146, v92, v148 row_shr:1 row_mask:0xf bank_mask:0xf bound_ctrl:1
	v_add_f32_dpp v108, v92, v108 row_shr:2 row_mask:0xf bank_mask:0xf bound_ctrl:1
	v_add_f32_dpp v166, v88, v168 row_shr:1 row_mask:0xf bank_mask:0xf bound_ctrl:1
	v_add_f32_dpp v162, v88, v164 row_shr:2 row_mask:0xf bank_mask:0xf bound_ctrl:1
	v_add_f32_dpp v147, v93, v149 row_shr:1 row_mask:0xf bank_mask:0xf bound_ctrl:1
	v_add_f32_dpp v109, v93, v109 row_shr:2 row_mask:0xf bank_mask:0xf bound_ctrl:1
	v_add_f32_dpp v167, v89, v169 row_shr:1 row_mask:0xf bank_mask:0xf bound_ctrl:1
	v_add_f32_dpp v163, v89, v165 row_shr:2 row_mask:0xf bank_mask:0xf bound_ctrl:1
	v_add_f32_dpp v150, v94, v160 row_shr:1 row_mask:0xf bank_mask:0xf bound_ctrl:1
	v_add_f32_dpp v104, v94, v110 row_shr:2 row_mask:0xf bank_mask:0xf bound_ctrl:1
	v_add_f32_dpp v172, v90, v174 row_shr:1 row_mask:0xf bank_mask:0xf bound_ctrl:1
	v_add_f32_dpp v106, v90, v106 row_shr:2 row_mask:0xf bank_mask:0xf bound_ctrl:1
	v_add_f32_dpp v151, v95, v161 row_shr:1 row_mask:0xf bank_mask:0xf bound_ctrl:1
	v_add_f32_dpp v105, v95, v111 row_shr:2 row_mask:0xf bank_mask:0xf bound_ctrl:1
	v_add_f32_dpp v173, v91, v175 row_shr:1 row_mask:0xf bank_mask:0xf bound_ctrl:1
	v_add_f32_dpp v107, v91, v107 row_shr:2 row_mask:0xf bank_mask:0xf bound_ctrl:1
	v_cmp_gt_i32_e64 s[14:15], s79, v195
	v_add_u32_e32 v195, s33, v195
	s_and_saveexec_b64 s[16:17], s[14:15]
	s_cbranch_execz .LBB0_2270
	s_waitcnt vmcnt(0)
	v_pk_fma_f32 v[104:105], v[126:127], v[104:105], v[130:131]
	v_pk_fma_f32 v[104:105], v[122:123], v[150:151], v[104:105]
	v_pk_fma_f32 v[108:109], v[124:125], v[108:109], v[128:129]
	v_pk_fma_f32 v[104:105], v[94:95], v[118:119], v[104:105]
	v_pk_fma_f32 v[108:109], v[120:121], v[146:147], v[108:109]
	v_mul_f32_e32 v144, 0xbfb8aa3b, v104
	v_mul_f32_e32 v145, 0xbfb8aa3b, v105
	v_pk_fma_f32 v[108:109], v[92:93], v[116:117], v[108:109]
	v_exp_f32_e32 v144, v144
	v_exp_f32_e32 v145, v145
	v_mul_f32_e32 v110, 0xbfb8aa3b, v108
	v_mul_f32_e32 v111, 0xbfb8aa3b, v109
	v_exp_f32_e32 v110, v110
	v_exp_f32_e32 v111, v111
	v_add_f32_e32 v144, 1.0, v144
	v_add_f32_e32 v145, 1.0, v145
	v_rcp_f32_e32 v144, v144
	v_rcp_f32_e32 v145, v145
	v_add_f32_e32 v110, 1.0, v110
	v_add_f32_e32 v111, 1.0, v111
	v_pk_fma_f32 v[106:107], v[138:139], v[106:107], v[142:143]
	v_rcp_f32_e32 v110, v110
	v_rcp_f32_e32 v111, v111
	v_pk_fma_f32 v[106:107], v[134:135], v[172:173], v[106:107]
	v_pk_fma_f32 v[162:163], v[136:137], v[162:163], v[140:141]
	v_pk_fma_f32 v[106:107], v[90:91], v[114:115], v[106:107]
	v_pk_mul_f32 v[104:105], v[104:105], v[144:145]
	v_pk_fma_f32 v[162:163], v[132:133], v[166:167], v[162:163]
	v_pk_mul_f32 v[104:105], v[106:107], v[104:105]
	v_pk_fma_f32 v[146:147], v[88:89], v[112:113], v[162:163]
	v_pk_mul_f32 v[108:109], v[108:109], v[110:111]
	v_cvt_pk_bf16_f32 v107, v104, v105
	v_mov_b64_e32 v[104:105], s[36:37]
	v_pk_mul_f32 v[108:109], v[146:147], v[108:109]
	v_mad_i64_i32 v[104:105], s[22:23], v195, s96, v[104:105]
	v_cvt_pk_bf16_f32 v106, v108, v109
	v_lshl_add_u64 v[104:105], v[190:191], 1, v[104:105]
	global_store_dwordx2 v[104:105], v[106:107], off
.LBB0_2270:
	s_or_b64 exec, exec, s[16:17]
	v_add_u32_e32 v168, s18, v227
	v_mov_b32_dpp v108, v92 row_shl:15 row_mask:0xf bank_mask:0xf bound_ctrl:1
	v_mov_b32_dpp v92, v92 row_shl:14 row_mask:0xf bank_mask:0xf bound_ctrl:1
	v_mov_b32_dpp v160, v88 row_shl:15 row_mask:0xf bank_mask:0xf bound_ctrl:1
	v_mov_b32_dpp v148, v88 row_shl:14 row_mask:0xf bank_mask:0xf bound_ctrl:1
	v_mov_b32_dpp v109, v93 row_shl:15 row_mask:0xf bank_mask:0xf bound_ctrl:1
	v_mov_b32_dpp v93, v93 row_shl:14 row_mask:0xf bank_mask:0xf bound_ctrl:1
	v_mov_b32_dpp v161, v89 row_shl:15 row_mask:0xf bank_mask:0xf bound_ctrl:1
	v_mov_b32_dpp v149, v89 row_shl:14 row_mask:0xf bank_mask:0xf bound_ctrl:1
	v_mov_b32_dpp v144, v94 row_shl:15 row_mask:0xf bank_mask:0xf bound_ctrl:1
	v_mov_b32_dpp v94, v94 row_shl:14 row_mask:0xf bank_mask:0xf bound_ctrl:1
	v_mov_b32_dpp v166, v90 row_shl:15 row_mask:0xf bank_mask:0xf bound_ctrl:1
	v_mov_b32_dpp v90, v90 row_shl:14 row_mask:0xf bank_mask:0xf bound_ctrl:1
	v_mov_b32_dpp v145, v95 row_shl:15 row_mask:0xf bank_mask:0xf bound_ctrl:1
	v_mov_b32_dpp v95, v95 row_shl:14 row_mask:0xf bank_mask:0xf bound_ctrl:1
	v_mov_b32_dpp v167, v91 row_shl:15 row_mask:0xf bank_mask:0xf bound_ctrl:1
	v_mov_b32_dpp v91, v91 row_shl:14 row_mask:0xf bank_mask:0xf bound_ctrl:1
	v_add_f32_dpp v106, v156, v108 row_shr:1 row_mask:0xf bank_mask:0xf bound_ctrl:1
	v_add_f32_dpp v92, v156, v92 row_shr:2 row_mask:0xf bank_mask:0xf bound_ctrl:1
	v_add_f32_dpp v150, v152, v160 row_shr:1 row_mask:0xf bank_mask:0xf bound_ctrl:1
	v_add_f32_dpp v146, v152, v148 row_shr:2 row_mask:0xf bank_mask:0xf bound_ctrl:1
	v_add_f32_dpp v107, v157, v109 row_shr:1 row_mask:0xf bank_mask:0xf bound_ctrl:1
	v_add_f32_dpp v93, v157, v93 row_shr:2 row_mask:0xf bank_mask:0xf bound_ctrl:1
	v_add_f32_dpp v151, v153, v161 row_shr:1 row_mask:0xf bank_mask:0xf bound_ctrl:1
	v_add_f32_dpp v147, v153, v149 row_shr:2 row_mask:0xf bank_mask:0xf bound_ctrl:1
	v_add_f32_dpp v110, v158, v144 row_shr:1 row_mask:0xf bank_mask:0xf bound_ctrl:1
	v_add_f32_dpp v88, v158, v94 row_shr:2 row_mask:0xf bank_mask:0xf bound_ctrl:1
	v_add_f32_dpp v164, v154, v166 row_shr:1 row_mask:0xf bank_mask:0xf bound_ctrl:1
	v_add_f32_dpp v90, v154, v90 row_shr:2 row_mask:0xf bank_mask:0xf bound_ctrl:1
	v_add_f32_dpp v111, v159, v145 row_shr:1 row_mask:0xf bank_mask:0xf bound_ctrl:1
	v_add_f32_dpp v89, v159, v95 row_shr:2 row_mask:0xf bank_mask:0xf bound_ctrl:1
	v_add_f32_dpp v165, v155, v167 row_shr:1 row_mask:0xf bank_mask:0xf bound_ctrl:1
	v_add_f32_dpp v91, v155, v91 row_shr:2 row_mask:0xf bank_mask:0xf bound_ctrl:1
	v_cmp_gt_i32_e64 s[22:23], s79, v168
	v_add_u32_e32 v168, s33, v168
	s_and_saveexec_b64 s[16:17], s[22:23]
	s_cbranch_execz .LBB0_2272
	s_waitcnt vmcnt(0)
	v_pk_fma_f32 v[88:89], v[126:127], v[88:89], v[130:131]
	v_pk_fma_f32 v[88:89], v[122:123], v[110:111], v[88:89]
	v_pk_fma_f32 v[92:93], v[124:125], v[92:93], v[128:129]
	v_pk_fma_f32 v[88:89], v[158:159], v[118:119], v[88:89]
	v_pk_fma_f32 v[92:93], v[120:121], v[106:107], v[92:93]
	v_mul_f32_e32 v104, 0xbfb8aa3b, v88
	v_mul_f32_e32 v105, 0xbfb8aa3b, v89
	v_pk_fma_f32 v[92:93], v[156:157], v[116:117], v[92:93]
	v_exp_f32_e32 v104, v104
	v_exp_f32_e32 v105, v105
	v_mul_f32_e32 v94, 0xbfb8aa3b, v92
	v_mul_f32_e32 v95, 0xbfb8aa3b, v93
	v_exp_f32_e32 v94, v94
	v_exp_f32_e32 v95, v95
	v_add_f32_e32 v104, 1.0, v104
	v_add_f32_e32 v105, 1.0, v105
	v_rcp_f32_e32 v104, v104
	v_rcp_f32_e32 v105, v105
	v_add_f32_e32 v94, 1.0, v94
	v_add_f32_e32 v95, 1.0, v95
	v_pk_fma_f32 v[90:91], v[138:139], v[90:91], v[142:143]
	v_rcp_f32_e32 v94, v94
	v_rcp_f32_e32 v95, v95
	v_pk_fma_f32 v[90:91], v[134:135], v[164:165], v[90:91]
	v_pk_fma_f32 v[146:147], v[136:137], v[146:147], v[140:141]
	v_pk_fma_f32 v[90:91], v[154:155], v[114:115], v[90:91]
	v_pk_mul_f32 v[88:89], v[88:89], v[104:105]
	v_pk_fma_f32 v[146:147], v[132:133], v[150:151], v[146:147]
	v_pk_mul_f32 v[88:89], v[90:91], v[88:89]
	v_pk_fma_f32 v[106:107], v[152:153], v[112:113], v[146:147]
	v_pk_mul_f32 v[92:93], v[92:93], v[94:95]
	v_cvt_pk_bf16_f32 v91, v88, v89
	v_mov_b64_e32 v[88:89], s[36:37]
	v_pk_mul_f32 v[92:93], v[106:107], v[92:93]
	v_mad_i64_i32 v[88:89], s[18:19], v168, s96, v[88:89]
	v_cvt_pk_bf16_f32 v90, v92, v93
	v_lshl_add_u64 v[88:89], v[190:191], 1, v[88:89]
	global_store_dwordx2 v[88:89], v[90:91], off

.LBB0_2280:
	s_or_b64 exec, exec, s[16:17]
	v_pk_mul_f32 v[78:79], v[78:79], v[194:195] op_sel_hi:[1,0]
	v_pk_mul_f32 v[76:77], v[76:77], v[194:195] op_sel_hi:[1,0]
	v_pk_mul_f32 v[66:67], v[66:67], v[194:195] op_sel_hi:[1,0]
	v_pk_mul_f32 v[64:65], v[64:65], v[194:195] op_sel_hi:[1,0]
	s_waitcnt lgkmcnt(0)
	v_mov_b32_dpp v92, v84 row_shl:15 row_mask:0xf bank_mask:0xf bound_ctrl:1
	v_mov_b32_dpp v84, v84 row_shl:14 row_mask:0xf bank_mask:0xf bound_ctrl:1
	v_mov_b32_dpp v144, v80 row_shl:15 row_mask:0xf bank_mask:0xf bound_ctrl:1
	v_mov_b32_dpp v108, v80 row_shl:14 row_mask:0xf bank_mask:0xf bound_ctrl:1
	v_mov_b32_dpp v93, v85 row_shl:15 row_mask:0xf bank_mask:0xf bound_ctrl:1
	v_mov_b32_dpp v85, v85 row_shl:14 row_mask:0xf bank_mask:0xf bound_ctrl:1
	v_mov_b32_dpp v145, v81 row_shl:15 row_mask:0xf bank_mask:0xf bound_ctrl:1
	v_mov_b32_dpp v109, v81 row_shl:14 row_mask:0xf bank_mask:0xf bound_ctrl:1
	v_mov_b32_dpp v104, v86 row_shl:15 row_mask:0xf bank_mask:0xf bound_ctrl:1
	v_mov_b32_dpp v86, v86 row_shl:14 row_mask:0xf bank_mask:0xf bound_ctrl:1
	v_mov_b32_dpp v150, v82 row_shl:15 row_mask:0xf bank_mask:0xf bound_ctrl:1
	v_mov_b32_dpp v82, v82 row_shl:14 row_mask:0xf bank_mask:0xf bound_ctrl:1
	v_mov_b32_dpp v105, v87 row_shl:15 row_mask:0xf bank_mask:0xf bound_ctrl:1
	v_mov_b32_dpp v87, v87 row_shl:14 row_mask:0xf bank_mask:0xf bound_ctrl:1
	v_mov_b32_dpp v151, v83 row_shl:15 row_mask:0xf bank_mask:0xf bound_ctrl:1
	v_mov_b32_dpp v83, v83 row_shl:14 row_mask:0xf bank_mask:0xf bound_ctrl:1
	v_add_f32_dpp v90, v76, v92 row_shr:1 row_mask:0xf bank_mask:0xf bound_ctrl:1
	v_add_f32_dpp v84, v76, v84 row_shr:2 row_mask:0xf bank_mask:0xf bound_ctrl:1
	v_add_f32_dpp v110, v64, v144 row_shr:1 row_mask:0xf bank_mask:0xf bound_ctrl:1
	v_add_f32_dpp v106, v64, v108 row_shr:2 row_mask:0xf bank_mask:0xf bound_ctrl:1
	v_add_f32_dpp v91, v77, v93 row_shr:1 row_mask:0xf bank_mask:0xf bound_ctrl:1
	v_add_f32_dpp v85, v77, v85 row_shr:2 row_mask:0xf bank_mask:0xf bound_ctrl:1
	v_add_f32_dpp v111, v65, v145 row_shr:1 row_mask:0xf bank_mask:0xf bound_ctrl:1
	v_add_f32_dpp v107, v65, v109 row_shr:2 row_mask:0xf bank_mask:0xf bound_ctrl:1
	v_add_f32_dpp v94, v78, v104 row_shr:1 row_mask:0xf bank_mask:0xf bound_ctrl:1
	v_add_f32_dpp v80, v78, v86 row_shr:2 row_mask:0xf bank_mask:0xf bound_ctrl:1
	v_add_f32_dpp v148, v66, v150 row_shr:1 row_mask:0xf bank_mask:0xf bound_ctrl:1
	v_add_f32_dpp v82, v66, v82 row_shr:2 row_mask:0xf bank_mask:0xf bound_ctrl:1
	v_add_f32_dpp v95, v79, v105 row_shr:1 row_mask:0xf bank_mask:0xf bound_ctrl:1
	v_add_f32_dpp v81, v79, v87 row_shr:2 row_mask:0xf bank_mask:0xf bound_ctrl:1
	v_add_f32_dpp v149, v67, v151 row_shr:1 row_mask:0xf bank_mask:0xf bound_ctrl:1
	v_add_f32_dpp v83, v67, v83 row_shr:2 row_mask:0xf bank_mask:0xf bound_ctrl:1
	v_cmp_gt_i32_e64 s[18:19], s79, v240
	v_add_u32_e32 v152, s33, v240
	s_and_saveexec_b64 s[16:17], s[18:19]
	s_cbranch_execz .LBB0_2282
	s_waitcnt vmcnt(0)
	v_pk_fma_f32 v[80:81], v[126:127], v[80:81], v[130:131]
	v_pk_fma_f32 v[80:81], v[122:123], v[94:95], v[80:81]
	v_pk_fma_f32 v[84:85], v[124:125], v[84:85], v[128:129]
	v_pk_fma_f32 v[80:81], v[78:79], v[118:119], v[80:81]
	v_pk_fma_f32 v[84:85], v[120:121], v[90:91], v[84:85]
	v_mul_f32_e32 v88, 0xbfb8aa3b, v80
	v_mul_f32_e32 v89, 0xbfb8aa3b, v81
	v_pk_fma_f32 v[84:85], v[76:77], v[116:117], v[84:85]
	v_exp_f32_e32 v88, v88
	v_exp_f32_e32 v89, v89
	v_mul_f32_e32 v86, 0xbfb8aa3b, v84
	v_mul_f32_e32 v87, 0xbfb8aa3b, v85
	v_exp_f32_e32 v86, v86
	v_exp_f32_e32 v87, v87
	v_add_f32_e32 v88, 1.0, v88
	v_add_f32_e32 v89, 1.0, v89
	v_rcp_f32_e32 v88, v88
	v_rcp_f32_e32 v89, v89
	v_add_f32_e32 v86, 1.0, v86
	v_add_f32_e32 v87, 1.0, v87
	v_pk_fma_f32 v[82:83], v[138:139], v[82:83], v[142:143]
	v_rcp_f32_e32 v86, v86
	v_rcp_f32_e32 v87, v87
	v_pk_fma_f32 v[82:83], v[134:135], v[148:149], v[82:83]
	v_pk_fma_f32 v[106:107], v[136:137], v[106:107], v[140:141]
	v_pk_fma_f32 v[82:83], v[66:67], v[114:115], v[82:83]
	v_pk_mul_f32 v[80:81], v[80:81], v[88:89]
	v_pk_fma_f32 v[106:107], v[132:133], v[110:111], v[106:107]
	v_pk_mul_f32 v[80:81], v[82:83], v[80:81]
	v_pk_fma_f32 v[90:91], v[64:65], v[112:113], v[106:107]
	v_pk_mul_f32 v[84:85], v[84:85], v[86:87]
	v_cvt_pk_bf16_f32 v83, v80, v81
	v_mov_b64_e32 v[80:81], s[36:37]
	v_pk_mul_f32 v[84:85], v[90:91], v[84:85]
	v_mad_i64_i32 v[80:81], s[26:27], v152, s96, v[80:81]
	v_cvt_pk_bf16_f32 v82, v84, v85
	v_lshl_add_u64 v[80:81], v[190:191], 1, v[80:81]
	global_store_dwordx2 v[80:81], v[82:83], off
.LBB0_2282:
	s_or_b64 exec, exec, s[16:17]
	v_pk_mul_f32 v[62:63], v[62:63], v[192:193] op_sel_hi:[1,0]
	v_pk_mul_f32 v[60:61], v[60:61], v[192:193] op_sel_hi:[1,0]
	v_pk_mul_f32 v[58:59], v[58:59], v[192:193] op_sel_hi:[1,0]
	v_pk_mul_f32 v[56:57], v[56:57], v[192:193] op_sel_hi:[1,0]
	v_mov_b32_dpp v84, v76 row_shl:15 row_mask:0xf bank_mask:0xf bound_ctrl:1
	v_mov_b32_dpp v76, v76 row_shl:14 row_mask:0xf bank_mask:0xf bound_ctrl:1
	v_mov_b32_dpp v104, v64 row_shl:15 row_mask:0xf bank_mask:0xf bound_ctrl:1
	v_mov_b32_dpp v92, v64 row_shl:14 row_mask:0xf bank_mask:0xf bound_ctrl:1
	v_mov_b32_dpp v85, v77 row_shl:15 row_mask:0xf bank_mask:0xf bound_ctrl:1
	v_mov_b32_dpp v77, v77 row_shl:14 row_mask:0xf bank_mask:0xf bound_ctrl:1
	v_mov_b32_dpp v105, v65 row_shl:15 row_mask:0xf bank_mask:0xf bound_ctrl:1
	v_mov_b32_dpp v93, v65 row_shl:14 row_mask:0xf bank_mask:0xf bound_ctrl:1
	v_mov_b32_dpp v88, v78 row_shl:15 row_mask:0xf bank_mask:0xf bound_ctrl:1
	v_mov_b32_dpp v78, v78 row_shl:14 row_mask:0xf bank_mask:0xf bound_ctrl:1
	v_mov_b32_dpp v110, v66 row_shl:15 row_mask:0xf bank_mask:0xf bound_ctrl:1
	v_mov_b32_dpp v66, v66 row_shl:14 row_mask:0xf bank_mask:0xf bound_ctrl:1
	v_mov_b32_dpp v89, v79 row_shl:15 row_mask:0xf bank_mask:0xf bound_ctrl:1
	v_mov_b32_dpp v79, v79 row_shl:14 row_mask:0xf bank_mask:0xf bound_ctrl:1
	v_mov_b32_dpp v111, v67 row_shl:15 row_mask:0xf bank_mask:0xf bound_ctrl:1
	v_mov_b32_dpp v67, v67 row_shl:14 row_mask:0xf bank_mask:0xf bound_ctrl:1
	v_add_f32_dpp v82, v60, v84 row_shr:1 row_mask:0xf bank_mask:0xf bound_ctrl:1
	v_add_f32_dpp v76, v60, v76 row_shr:2 row_mask:0xf bank_mask:0xf bound_ctrl:1
	v_add_f32_dpp v94, v56, v104 row_shr:1 row_mask:0xf bank_mask:0xf bound_ctrl:1
	v_add_f32_dpp v90, v56, v92 row_shr:2 row_mask:0xf bank_mask:0xf bound_ctrl:1
	v_add_f32_dpp v83, v61, v85 row_shr:1 row_mask:0xf bank_mask:0xf bound_ctrl:1
	v_add_f32_dpp v77, v61, v77 row_shr:2 row_mask:0xf bank_mask:0xf bound_ctrl:1
	v_add_f32_dpp v95, v57, v105 row_shr:1 row_mask:0xf bank_mask:0xf bound_ctrl:1
	v_add_f32_dpp v91, v57, v93 row_shr:2 row_mask:0xf bank_mask:0xf bound_ctrl:1
	v_add_f32_dpp v86, v62, v88 row_shr:1 row_mask:0xf bank_mask:0xf bound_ctrl:1
	v_add_f32_dpp v64, v62, v78 row_shr:2 row_mask:0xf bank_mask:0xf bound_ctrl:1
	v_add_f32_dpp v108, v58, v110 row_shr:1 row_mask:0xf bank_mask:0xf bound_ctrl:1
	v_add_f32_dpp v66, v58, v66 row_shr:2 row_mask:0xf bank_mask:0xf bound_ctrl:1
	v_add_f32_dpp v87, v63, v89 row_shr:1 row_mask:0xf bank_mask:0xf bound_ctrl:1
	v_add_f32_dpp v65, v63, v79 row_shr:2 row_mask:0xf bank_mask:0xf bound_ctrl:1
	v_add_f32_dpp v109, v59, v111 row_shr:1 row_mask:0xf bank_mask:0xf bound_ctrl:1
	v_add_f32_dpp v67, v59, v67 row_shr:2 row_mask:0xf bank_mask:0xf bound_ctrl:1
	v_cmp_gt_i32_e64 s[16:17], s79, v203
	v_add_u32_e32 v144, s33, v203
	s_and_saveexec_b64 s[26:27], s[16:17]
	s_cbranch_execz .LBB0_2284
	s_waitcnt vmcnt(0)
	v_pk_fma_f32 v[64:65], v[126:127], v[64:65], v[130:131]
	v_pk_fma_f32 v[64:65], v[122:123], v[86:87], v[64:65]
	v_pk_fma_f32 v[76:77], v[124:125], v[76:77], v[128:129]
	v_pk_fma_f32 v[64:65], v[62:63], v[118:119], v[64:65]
	v_pk_fma_f32 v[76:77], v[120:121], v[82:83], v[76:77]
	v_mul_f32_e32 v80, 0xbfb8aa3b, v64
	v_mul_f32_e32 v81, 0xbfb8aa3b, v65
	v_pk_fma_f32 v[76:77], v[60:61], v[116:117], v[76:77]
	v_exp_f32_e32 v80, v80
	v_exp_f32_e32 v81, v81
	v_mul_f32_e32 v78, 0xbfb8aa3b, v76
	v_mul_f32_e32 v79, 0xbfb8aa3b, v77
	v_exp_f32_e32 v78, v78
	v_exp_f32_e32 v79, v79
	v_add_f32_e32 v80, 1.0, v80
	v_add_f32_e32 v81, 1.0, v81
	v_rcp_f32_e32 v80, v80
	v_rcp_f32_e32 v81, v81
	v_add_f32_e32 v78, 1.0, v78
	v_add_f32_e32 v79, 1.0, v79
	v_pk_fma_f32 v[66:67], v[138:139], v[66:67], v[142:143]
	v_rcp_f32_e32 v78, v78
	v_rcp_f32_e32 v79, v79
	v_pk_fma_f32 v[66:67], v[134:135], v[108:109], v[66:67]
	v_pk_fma_f32 v[90:91], v[136:137], v[90:91], v[140:141]
	v_pk_fma_f32 v[66:67], v[58:59], v[114:115], v[66:67]
	v_pk_mul_f32 v[64:65], v[64:65], v[80:81]
	v_pk_fma_f32 v[90:91], v[132:133], v[94:95], v[90:91]
	v_pk_mul_f32 v[64:65], v[66:67], v[64:65]
	v_pk_fma_f32 v[82:83], v[56:57], v[112:113], v[90:91]
	v_pk_mul_f32 v[76:77], v[76:77], v[78:79]
	v_cvt_pk_bf16_f32 v67, v64, v65
	v_mov_b64_e32 v[64:65], s[36:37]
	v_pk_mul_f32 v[76:77], v[82:83], v[76:77]
	v_mad_i64_i32 v[64:65], s[70:71], v144, s96, v[64:65]
	v_cvt_pk_bf16_f32 v66, v76, v77
	v_lshl_add_u64 v[64:65], v[190:191], 1, v[64:65]
	global_store_dwordx2 v[64:65], v[66:67], off
.LBB0_2284:
	s_or_b64 exec, exec, s[26:27]
	v_mov_b32_dpp v76, v60 row_shl:15 row_mask:0xf bank_mask:0xf bound_ctrl:1
	v_mov_b32_dpp v60, v60 row_shl:14 row_mask:0xf bank_mask:0xf bound_ctrl:1
	v_mov_b32_dpp v88, v56 row_shl:15 row_mask:0xf bank_mask:0xf bound_ctrl:1
	v_mov_b32_dpp v84, v56 row_shl:14 row_mask:0xf bank_mask:0xf bound_ctrl:1
	v_mov_b32_dpp v77, v61 row_shl:15 row_mask:0xf bank_mask:0xf bound_ctrl:1
	v_mov_b32_dpp v61, v61 row_shl:14 row_mask:0xf bank_mask:0xf bound_ctrl:1
	v_mov_b32_dpp v89, v57 row_shl:15 row_mask:0xf bank_mask:0xf bound_ctrl:1
	v_mov_b32_dpp v85, v57 row_shl:14 row_mask:0xf bank_mask:0xf bound_ctrl:1
	v_mov_b32_dpp v80, v62 row_shl:15 row_mask:0xf bank_mask:0xf bound_ctrl:1
	v_mov_b32_dpp v62, v62 row_shl:14 row_mask:0xf bank_mask:0xf bound_ctrl:1
	v_mov_b32_dpp v94, v58 row_shl:15 row_mask:0xf bank_mask:0xf bound_ctrl:1
	v_mov_b32_dpp v58, v58 row_shl:14 row_mask:0xf bank_mask:0xf bound_ctrl:1
	v_mov_b32_dpp v81, v63 row_shl:15 row_mask:0xf bank_mask:0xf bound_ctrl:1
	v_mov_b32_dpp v63, v63 row_shl:14 row_mask:0xf bank_mask:0xf bound_ctrl:1
	v_mov_b32_dpp v95, v59 row_shl:15 row_mask:0xf bank_mask:0xf bound_ctrl:1
	v_mov_b32_dpp v59, v59 row_shl:14 row_mask:0xf bank_mask:0xf bound_ctrl:1
	v_add_f32_dpp v66, v100, v76 row_shr:1 row_mask:0xf bank_mask:0xf bound_ctrl:1
	v_add_f32_dpp v60, v100, v60 row_shr:2 row_mask:0xf bank_mask:0xf bound_ctrl:1
	v_add_f32_dpp v86, v96, v88 row_shr:1 row_mask:0xf bank_mask:0xf bound_ctrl:1
	v_add_f32_dpp v82, v96, v84 row_shr:2 row_mask:0xf bank_mask:0xf bound_ctrl:1
	v_add_f32_dpp v67, v101, v77 row_shr:1 row_mask:0xf bank_mask:0xf bound_ctrl:1
	v_add_f32_dpp v61, v101, v61 row_shr:2 row_mask:0xf bank_mask:0xf bound_ctrl:1
	v_add_f32_dpp v87, v97, v89 row_shr:1 row_mask:0xf bank_mask:0xf bound_ctrl:1
	v_add_f32_dpp v83, v97, v85 row_shr:2 row_mask:0xf bank_mask:0xf bound_ctrl:1
	v_add_f32_dpp v78, v102, v80 row_shr:1 row_mask:0xf bank_mask:0xf bound_ctrl:1
	v_add_f32_dpp v56, v102, v62 row_shr:2 row_mask:0xf bank_mask:0xf bound_ctrl:1
	v_add_f32_dpp v92, v98, v94 row_shr:1 row_mask:0xf bank_mask:0xf bound_ctrl:1
	v_add_f32_dpp v58, v98, v58 row_shr:2 row_mask:0xf bank_mask:0xf bound_ctrl:1
	v_add_f32_dpp v79, v103, v81 row_shr:1 row_mask:0xf bank_mask:0xf bound_ctrl:1
	v_add_f32_dpp v57, v103, v63 row_shr:2 row_mask:0xf bank_mask:0xf bound_ctrl:1
	v_add_f32_dpp v93, v99, v95 row_shr:1 row_mask:0xf bank_mask:0xf bound_ctrl:1
	v_add_f32_dpp v59, v99, v59 row_shr:2 row_mask:0xf bank_mask:0xf bound_ctrl:1
	v_cmp_gt_i32_e64 s[26:27], s79, v201
	v_add_u32_e32 v145, s33, v201
	s_and_saveexec_b64 s[70:71], s[26:27]
	s_cbranch_execz .LBB0_2286
	s_waitcnt vmcnt(0)
	v_pk_fma_f32 v[56:57], v[126:127], v[56:57], v[130:131]
	v_pk_fma_f32 v[56:57], v[122:123], v[78:79], v[56:57]
	v_pk_fma_f32 v[60:61], v[124:125], v[60:61], v[128:129]
	v_pk_fma_f32 v[56:57], v[102:103], v[118:119], v[56:57]
	v_pk_fma_f32 v[60:61], v[120:121], v[66:67], v[60:61]
	v_mul_f32_e32 v64, 0xbfb8aa3b, v56
	v_mul_f32_e32 v65, 0xbfb8aa3b, v57
	v_pk_fma_f32 v[60:61], v[100:101], v[116:117], v[60:61]
	v_exp_f32_e32 v64, v64
	v_exp_f32_e32 v65, v65
	v_mul_f32_e32 v62, 0xbfb8aa3b, v60
	v_mul_f32_e32 v63, 0xbfb8aa3b, v61
	v_exp_f32_e32 v62, v62
	v_exp_f32_e32 v63, v63
	v_add_f32_e32 v64, 1.0, v64
	v_add_f32_e32 v65, 1.0, v65
	v_rcp_f32_e32 v64, v64
	v_rcp_f32_e32 v65, v65
	v_add_f32_e32 v62, 1.0, v62
	v_add_f32_e32 v63, 1.0, v63
	v_pk_fma_f32 v[58:59], v[138:139], v[58:59], v[142:143]
	v_rcp_f32_e32 v62, v62
	v_rcp_f32_e32 v63, v63
	v_pk_fma_f32 v[58:59], v[134:135], v[92:93], v[58:59]
	v_pk_fma_f32 v[82:83], v[136:137], v[82:83], v[140:141]
	v_pk_fma_f32 v[58:59], v[98:99], v[114:115], v[58:59]
	v_pk_mul_f32 v[56:57], v[56:57], v[64:65]
	v_pk_fma_f32 v[82:83], v[132:133], v[86:87], v[82:83]
	v_pk_mul_f32 v[56:57], v[58:59], v[56:57]
	v_pk_fma_f32 v[66:67], v[96:97], v[112:113], v[82:83]
	v_pk_mul_f32 v[60:61], v[60:61], v[62:63]
	v_cvt_pk_bf16_f32 v59, v56, v57
	v_mov_b64_e32 v[56:57], s[36:37]
	v_pk_mul_f32 v[60:61], v[66:67], v[60:61]
	v_mad_i64_i32 v[56:57], vcc, v145, s96, v[56:57]
	v_cvt_pk_bf16_f32 v58, v60, v61
	v_lshl_add_u64 v[56:57], v[190:191], 1, v[56:57]
	global_store_dwordx2 v[56:57], v[58:59], off

.LBB0_2296:
	s_or_b64 exec, exec, s[20:21]
	v_mov_b32_e32 v201, v200
	v_mov_b32_e32 v96, v200
	v_mov_b32_e32 v97, v200
	v_pk_mul_f32 v[46:47], v[46:47], v[96:97]
	v_pk_mul_f32 v[44:45], v[44:45], v[200:201]
	v_pk_mul_f32 v[34:35], v[34:35], v[96:97]
	v_pk_mul_f32 v[32:33], v[32:33], v[200:201]
	v_mov_b32_dpp v100, v52 row_shl:15 row_mask:0xf bank_mask:0xf bound_ctrl:1
	v_mov_b32_dpp v52, v52 row_shl:14 row_mask:0xf bank_mask:0xf bound_ctrl:1
	v_mov_b32_dpp v112, v48 row_shl:15 row_mask:0xf bank_mask:0xf bound_ctrl:1
	v_mov_b32_dpp v108, v48 row_shl:14 row_mask:0xf bank_mask:0xf bound_ctrl:1
	v_mov_b32_dpp v101, v53 row_shl:15 row_mask:0xf bank_mask:0xf bound_ctrl:1
	v_mov_b32_dpp v53, v53 row_shl:14 row_mask:0xf bank_mask:0xf bound_ctrl:1
	v_mov_b32_dpp v113, v49 row_shl:15 row_mask:0xf bank_mask:0xf bound_ctrl:1
	v_mov_b32_dpp v109, v49 row_shl:14 row_mask:0xf bank_mask:0xf bound_ctrl:1
	v_mov_b32_dpp v104, v54 row_shl:15 row_mask:0xf bank_mask:0xf bound_ctrl:1
	v_mov_b32_dpp v54, v54 row_shl:14 row_mask:0xf bank_mask:0xf bound_ctrl:1
	v_mov_b32_dpp v118, v50 row_shl:15 row_mask:0xf bank_mask:0xf bound_ctrl:1
	v_mov_b32_dpp v50, v50 row_shl:14 row_mask:0xf bank_mask:0xf bound_ctrl:1
	v_mov_b32_dpp v105, v55 row_shl:15 row_mask:0xf bank_mask:0xf bound_ctrl:1
	v_mov_b32_dpp v55, v55 row_shl:14 row_mask:0xf bank_mask:0xf bound_ctrl:1
	v_mov_b32_dpp v119, v51 row_shl:15 row_mask:0xf bank_mask:0xf bound_ctrl:1
	v_mov_b32_dpp v51, v51 row_shl:14 row_mask:0xf bank_mask:0xf bound_ctrl:1
	v_add_f32_dpp v98, v44, v100 row_shr:1 row_mask:0xf bank_mask:0xf bound_ctrl:1
	v_add_f32_dpp v52, v44, v52 row_shr:2 row_mask:0xf bank_mask:0xf bound_ctrl:1
	v_add_f32_dpp v110, v32, v112 row_shr:1 row_mask:0xf bank_mask:0xf bound_ctrl:1
	v_add_f32_dpp v106, v32, v108 row_shr:2 row_mask:0xf bank_mask:0xf bound_ctrl:1
	v_add_f32_dpp v99, v45, v101 row_shr:1 row_mask:0xf bank_mask:0xf bound_ctrl:1
	v_add_f32_dpp v53, v45, v53 row_shr:2 row_mask:0xf bank_mask:0xf bound_ctrl:1
	v_add_f32_dpp v111, v33, v113 row_shr:1 row_mask:0xf bank_mask:0xf bound_ctrl:1
	v_add_f32_dpp v107, v33, v109 row_shr:2 row_mask:0xf bank_mask:0xf bound_ctrl:1
	v_add_f32_dpp v102, v46, v104 row_shr:1 row_mask:0xf bank_mask:0xf bound_ctrl:1
	v_add_f32_dpp v48, v46, v54 row_shr:2 row_mask:0xf bank_mask:0xf bound_ctrl:1
	v_add_f32_dpp v116, v34, v118 row_shr:1 row_mask:0xf bank_mask:0xf bound_ctrl:1
	v_add_f32_dpp v50, v34, v50 row_shr:2 row_mask:0xf bank_mask:0xf bound_ctrl:1
	v_add_f32_dpp v103, v47, v105 row_shr:1 row_mask:0xf bank_mask:0xf bound_ctrl:1
	v_add_f32_dpp v49, v47, v55 row_shr:2 row_mask:0xf bank_mask:0xf bound_ctrl:1
	v_add_f32_dpp v117, v35, v119 row_shr:1 row_mask:0xf bank_mask:0xf bound_ctrl:1
	v_add_f32_dpp v51, v35, v51 row_shr:2 row_mask:0xf bank_mask:0xf bound_ctrl:1
	s_and_saveexec_b64 s[0:1], s[12:13]
	s_cbranch_execz .LBB0_2298
	v_pk_fma_f32 v[48:49], v[78:79], v[48:49], v[82:83]
	v_pk_fma_f32 v[48:49], v[66:67], v[102:103], v[48:49]
	v_pk_fma_f32 v[52:53], v[76:77], v[52:53], v[80:81]
	v_pk_fma_f32 v[48:49], v[46:47], v[62:63], v[48:49]
	v_pk_fma_f32 v[52:53], v[64:65], v[98:99], v[52:53]
	v_mul_f32_e32 v96, 0xbfb8aa3b, v48
	v_mul_f32_e32 v97, 0xbfb8aa3b, v49
	v_pk_fma_f32 v[52:53], v[44:45], v[60:61], v[52:53]
	v_exp_f32_e32 v96, v96
	v_exp_f32_e32 v97, v97
	v_mul_f32_e32 v54, 0xbfb8aa3b, v52
	v_mul_f32_e32 v55, 0xbfb8aa3b, v53
	v_exp_f32_e32 v54, v54
	v_exp_f32_e32 v55, v55
	v_add_f32_e32 v96, 1.0, v96
	v_add_f32_e32 v97, 1.0, v97
	v_rcp_f32_e32 v96, v96
	v_rcp_f32_e32 v97, v97
	v_add_f32_e32 v54, 1.0, v54
	v_add_f32_e32 v55, 1.0, v55
	v_pk_fma_f32 v[50:51], v[90:91], v[50:51], v[94:95]
	v_rcp_f32_e32 v54, v54
	v_rcp_f32_e32 v55, v55
	v_pk_fma_f32 v[50:51], v[86:87], v[116:117], v[50:51]
	v_pk_fma_f32 v[106:107], v[88:89], v[106:107], v[92:93]
	v_pk_fma_f32 v[50:51], v[34:35], v[58:59], v[50:51]
	v_pk_mul_f32 v[48:49], v[48:49], v[96:97]
	v_pk_fma_f32 v[106:107], v[84:85], v[110:111], v[106:107]
	v_pk_mul_f32 v[48:49], v[50:51], v[48:49]
	v_pk_fma_f32 v[98:99], v[32:33], v[56:57], v[106:107]
	v_pk_mul_f32 v[52:53], v[52:53], v[54:55]
	v_cvt_pk_bf16_f32 v51, v48, v49
	v_mov_b64_e32 v[48:49], s[36:37]
	v_pk_mul_f32 v[52:53], v[98:99], v[52:53]
	v_mad_i64_i32 v[48:49], s[12:13], v197, s96, v[48:49]
	v_cvt_pk_bf16_f32 v50, v52, v53
	v_lshl_add_u64 v[48:49], v[190:191], 1, v[48:49]
	global_store_dwordx2 v[48:49], v[50:51], off offset:8
.LBB0_2298:
	s_or_b64 exec, exec, s[0:1]
	v_mov_b32_e32 v199, v198
	v_mov_b32_e32 v48, v198
	v_mov_b32_e32 v49, v198
	v_pk_mul_f32 v[30:31], v[30:31], v[48:49]
	v_pk_mul_f32 v[28:29], v[28:29], v[198:199]
	v_pk_mul_f32 v[26:27], v[26:27], v[48:49]
	v_pk_mul_f32 v[24:25], v[24:25], v[198:199]
	v_mov_b32_dpp v52, v44 row_shl:15 row_mask:0xf bank_mask:0xf bound_ctrl:1
	v_mov_b32_dpp v44, v44 row_shl:14 row_mask:0xf bank_mask:0xf bound_ctrl:1
	v_mov_b32_dpp v104, v32 row_shl:15 row_mask:0xf bank_mask:0xf bound_ctrl:1
	v_mov_b32_dpp v100, v32 row_shl:14 row_mask:0xf bank_mask:0xf bound_ctrl:1
	v_mov_b32_dpp v53, v45 row_shl:15 row_mask:0xf bank_mask:0xf bound_ctrl:1
	v_mov_b32_dpp v45, v45 row_shl:14 row_mask:0xf bank_mask:0xf bound_ctrl:1
	v_mov_b32_dpp v105, v33 row_shl:15 row_mask:0xf bank_mask:0xf bound_ctrl:1
	v_mov_b32_dpp v101, v33 row_shl:14 row_mask:0xf bank_mask:0xf bound_ctrl:1
	v_mov_b32_dpp v96, v46 row_shl:15 row_mask:0xf bank_mask:0xf bound_ctrl:1
	v_mov_b32_dpp v46, v46 row_shl:14 row_mask:0xf bank_mask:0xf bound_ctrl:1
	v_mov_b32_dpp v110, v34 row_shl:15 row_mask:0xf bank_mask:0xf bound_ctrl:1
	v_mov_b32_dpp v34, v34 row_shl:14 row_mask:0xf bank_mask:0xf bound_ctrl:1
	v_mov_b32_dpp v97, v47 row_shl:15 row_mask:0xf bank_mask:0xf bound_ctrl:1
	v_mov_b32_dpp v47, v47 row_shl:14 row_mask:0xf bank_mask:0xf bound_ctrl:1
	v_mov_b32_dpp v111, v35 row_shl:15 row_mask:0xf bank_mask:0xf bound_ctrl:1
	v_mov_b32_dpp v35, v35 row_shl:14 row_mask:0xf bank_mask:0xf bound_ctrl:1
	v_add_f32_dpp v50, v28, v52 row_shr:1 row_mask:0xf bank_mask:0xf bound_ctrl:1
	v_add_f32_dpp v44, v28, v44 row_shr:2 row_mask:0xf bank_mask:0xf bound_ctrl:1
	v_add_f32_dpp v102, v24, v104 row_shr:1 row_mask:0xf bank_mask:0xf bound_ctrl:1
	v_add_f32_dpp v98, v24, v100 row_shr:2 row_mask:0xf bank_mask:0xf bound_ctrl:1
	v_add_f32_dpp v51, v29, v53 row_shr:1 row_mask:0xf bank_mask:0xf bound_ctrl:1
	v_add_f32_dpp v45, v29, v45 row_shr:2 row_mask:0xf bank_mask:0xf bound_ctrl:1
	v_add_f32_dpp v103, v25, v105 row_shr:1 row_mask:0xf bank_mask:0xf bound_ctrl:1
	v_add_f32_dpp v99, v25, v101 row_shr:2 row_mask:0xf bank_mask:0xf bound_ctrl:1
	v_add_f32_dpp v54, v30, v96 row_shr:1 row_mask:0xf bank_mask:0xf bound_ctrl:1
	v_add_f32_dpp v32, v30, v46 row_shr:2 row_mask:0xf bank_mask:0xf bound_ctrl:1
	v_add_f32_dpp v108, v26, v110 row_shr:1 row_mask:0xf bank_mask:0xf bound_ctrl:1
	v_add_f32_dpp v34, v26, v34 row_shr:2 row_mask:0xf bank_mask:0xf bound_ctrl:1
	v_add_f32_dpp v55, v31, v97 row_shr:1 row_mask:0xf bank_mask:0xf bound_ctrl:1
	v_add_f32_dpp v33, v31, v47 row_shr:2 row_mask:0xf bank_mask:0xf bound_ctrl:1
	v_add_f32_dpp v109, v27, v111 row_shr:1 row_mask:0xf bank_mask:0xf bound_ctrl:1
	v_add_f32_dpp v35, v27, v35 row_shr:2 row_mask:0xf bank_mask:0xf bound_ctrl:1
	s_and_saveexec_b64 s[0:1], s[14:15]
	s_cbranch_execz .LBB0_2300
	v_pk_fma_f32 v[32:33], v[78:79], v[32:33], v[82:83]
	v_pk_fma_f32 v[32:33], v[66:67], v[54:55], v[32:33]
	v_pk_fma_f32 v[44:45], v[76:77], v[44:45], v[80:81]
	v_pk_fma_f32 v[32:33], v[30:31], v[62:63], v[32:33]
	v_pk_fma_f32 v[44:45], v[64:65], v[50:51], v[44:45]
	v_mul_f32_e32 v48, 0xbfb8aa3b, v32
	v_mul_f32_e32 v49, 0xbfb8aa3b, v33
	v_pk_fma_f32 v[44:45], v[28:29], v[60:61], v[44:45]
	v_exp_f32_e32 v48, v48
	v_exp_f32_e32 v49, v49
	v_mul_f32_e32 v46, 0xbfb8aa3b, v44
	v_mul_f32_e32 v47, 0xbfb8aa3b, v45
	v_exp_f32_e32 v46, v46
	v_exp_f32_e32 v47, v47
	v_add_f32_e32 v48, 1.0, v48
	v_add_f32_e32 v49, 1.0, v49
	v_rcp_f32_e32 v48, v48
	v_rcp_f32_e32 v49, v49
	v_add_f32_e32 v46, 1.0, v46
	v_add_f32_e32 v47, 1.0, v47
	v_pk_fma_f32 v[34:35], v[90:91], v[34:35], v[94:95]
	v_rcp_f32_e32 v46, v46
	v_rcp_f32_e32 v47, v47
	v_pk_fma_f32 v[34:35], v[86:87], v[108:109], v[34:35]
	v_pk_fma_f32 v[98:99], v[88:89], v[98:99], v[92:93]
	v_pk_fma_f32 v[34:35], v[26:27], v[58:59], v[34:35]
	v_pk_mul_f32 v[32:33], v[32:33], v[48:49]
	v_pk_fma_f32 v[98:99], v[84:85], v[102:103], v[98:99]
	v_pk_mul_f32 v[32:33], v[34:35], v[32:33]
	v_pk_fma_f32 v[50:51], v[24:25], v[56:57], v[98:99]
	v_pk_mul_f32 v[44:45], v[44:45], v[46:47]
	v_cvt_pk_bf16_f32 v35, v32, v33
	v_mov_b64_e32 v[32:33], s[36:37]
	v_pk_mul_f32 v[44:45], v[50:51], v[44:45]
	v_mad_i64_i32 v[32:33], s[12:13], v195, s96, v[32:33]
	v_cvt_pk_bf16_f32 v34, v44, v45
	v_lshl_add_u64 v[32:33], v[190:191], 1, v[32:33]
	global_store_dwordx2 v[32:33], v[34:35], off offset:8
.LBB0_2300:
	s_or_b64 exec, exec, s[0:1]
	v_mov_b32_dpp v44, v28 row_shl:15 row_mask:0xf bank_mask:0xf bound_ctrl:1
	v_mov_b32_dpp v28, v28 row_shl:14 row_mask:0xf bank_mask:0xf bound_ctrl:1
	v_mov_b32_dpp v96, v24 row_shl:15 row_mask:0xf bank_mask:0xf bound_ctrl:1
	v_mov_b32_dpp v52, v24 row_shl:14 row_mask:0xf bank_mask:0xf bound_ctrl:1
	v_mov_b32_dpp v45, v29 row_shl:15 row_mask:0xf bank_mask:0xf bound_ctrl:1
	v_mov_b32_dpp v29, v29 row_shl:14 row_mask:0xf bank_mask:0xf bound_ctrl:1
	v_mov_b32_dpp v97, v25 row_shl:15 row_mask:0xf bank_mask:0xf bound_ctrl:1
	v_mov_b32_dpp v53, v25 row_shl:14 row_mask:0xf bank_mask:0xf bound_ctrl:1
	v_mov_b32_dpp v48, v30 row_shl:15 row_mask:0xf bank_mask:0xf bound_ctrl:1
	v_mov_b32_dpp v30, v30 row_shl:14 row_mask:0xf bank_mask:0xf bound_ctrl:1
	v_mov_b32_dpp v102, v26 row_shl:15 row_mask:0xf bank_mask:0xf bound_ctrl:1
	v_mov_b32_dpp v26, v26 row_shl:14 row_mask:0xf bank_mask:0xf bound_ctrl:1
	v_mov_b32_dpp v49, v31 row_shl:15 row_mask:0xf bank_mask:0xf bound_ctrl:1
	v_mov_b32_dpp v31, v31 row_shl:14 row_mask:0xf bank_mask:0xf bound_ctrl:1
	v_mov_b32_dpp v103, v27 row_shl:15 row_mask:0xf bank_mask:0xf bound_ctrl:1
	v_mov_b32_dpp v27, v27 row_shl:14 row_mask:0xf bank_mask:0xf bound_ctrl:1
	v_add_f32_dpp v34, v72, v44 row_shr:1 row_mask:0xf bank_mask:0xf bound_ctrl:1
	v_add_f32_dpp v28, v72, v28 row_shr:2 row_mask:0xf bank_mask:0xf bound_ctrl:1
	v_add_f32_dpp v54, v68, v96 row_shr:1 row_mask:0xf bank_mask:0xf bound_ctrl:1
	v_add_f32_dpp v50, v68, v52 row_shr:2 row_mask:0xf bank_mask:0xf bound_ctrl:1
	v_add_f32_dpp v35, v73, v45 row_shr:1 row_mask:0xf bank_mask:0xf bound_ctrl:1
	v_add_f32_dpp v29, v73, v29 row_shr:2 row_mask:0xf bank_mask:0xf bound_ctrl:1
	v_add_f32_dpp v55, v69, v97 row_shr:1 row_mask:0xf bank_mask:0xf bound_ctrl:1
	v_add_f32_dpp v51, v69, v53 row_shr:2 row_mask:0xf bank_mask:0xf bound_ctrl:1
	v_add_f32_dpp v46, v74, v48 row_shr:1 row_mask:0xf bank_mask:0xf bound_ctrl:1
	v_add_f32_dpp v24, v74, v30 row_shr:2 row_mask:0xf bank_mask:0xf bound_ctrl:1
	v_add_f32_dpp v100, v70, v102 row_shr:1 row_mask:0xf bank_mask:0xf bound_ctrl:1
	v_add_f32_dpp v26, v70, v26 row_shr:2 row_mask:0xf bank_mask:0xf bound_ctrl:1
	v_add_f32_dpp v47, v75, v49 row_shr:1 row_mask:0xf bank_mask:0xf bound_ctrl:1
	v_add_f32_dpp v25, v75, v31 row_shr:2 row_mask:0xf bank_mask:0xf bound_ctrl:1
	v_add_f32_dpp v101, v71, v103 row_shr:1 row_mask:0xf bank_mask:0xf bound_ctrl:1
	v_add_f32_dpp v27, v71, v27 row_shr:2 row_mask:0xf bank_mask:0xf bound_ctrl:1
	s_and_saveexec_b64 s[0:1], s[22:23]
	s_cbranch_execz .LBB0_2302
	v_pk_fma_f32 v[24:25], v[78:79], v[24:25], v[82:83]
	v_pk_fma_f32 v[24:25], v[66:67], v[46:47], v[24:25]
	v_pk_fma_f32 v[28:29], v[76:77], v[28:29], v[80:81]
	v_pk_fma_f32 v[24:25], v[74:75], v[62:63], v[24:25]
	v_pk_fma_f32 v[28:29], v[64:65], v[34:35], v[28:29]
	v_mul_f32_e32 v32, 0xbfb8aa3b, v24
	v_mul_f32_e32 v33, 0xbfb8aa3b, v25
	v_pk_fma_f32 v[28:29], v[72:73], v[60:61], v[28:29]
	v_exp_f32_e32 v32, v32
	v_exp_f32_e32 v33, v33
	v_mul_f32_e32 v30, 0xbfb8aa3b, v28
	v_mul_f32_e32 v31, 0xbfb8aa3b, v29
	v_exp_f32_e32 v30, v30
	v_exp_f32_e32 v31, v31
	v_add_f32_e32 v32, 1.0, v32
	v_add_f32_e32 v33, 1.0, v33
	v_rcp_f32_e32 v32, v32
	v_rcp_f32_e32 v33, v33
	v_add_f32_e32 v30, 1.0, v30
	v_add_f32_e32 v31, 1.0, v31
	v_pk_fma_f32 v[26:27], v[90:91], v[26:27], v[94:95]
	v_rcp_f32_e32 v30, v30
	v_rcp_f32_e32 v31, v31
	v_pk_fma_f32 v[26:27], v[86:87], v[100:101], v[26:27]
	v_pk_fma_f32 v[50:51], v[88:89], v[50:51], v[92:93]
	v_pk_fma_f32 v[26:27], v[70:71], v[58:59], v[26:27]
	v_pk_mul_f32 v[24:25], v[24:25], v[32:33]
	v_pk_fma_f32 v[50:51], v[84:85], v[54:55], v[50:51]
	v_pk_mul_f32 v[24:25], v[26:27], v[24:25]
	v_pk_fma_f32 v[34:35], v[68:69], v[56:57], v[50:51]
	v_pk_mul_f32 v[28:29], v[28:29], v[30:31]
	v_cvt_pk_bf16_f32 v27, v24, v25
	v_mov_b64_e32 v[24:25], s[36:37]
	v_pk_mul_f32 v[28:29], v[34:35], v[28:29]
	v_mad_i64_i32 v[24:25], s[12:13], v168, s96, v[24:25]
	v_cvt_pk_bf16_f32 v26, v28, v29
	v_lshl_add_u64 v[24:25], v[190:191], 1, v[24:25]
	global_store_dwordx2 v[24:25], v[26:27], off offset:8

.LBB0_2310:
	s_or_b64 exec, exec, s[0:1]
	v_mov_b32_e32 v195, v194
	v_mov_b32_e32 v24, v194
	v_mov_b32_e32 v25, v194
	v_pk_mul_f32 v[14:15], v[14:15], v[24:25]
	v_pk_mul_f32 v[12:13], v[12:13], v[194:195]
	v_pk_mul_f32 v[10:11], v[10:11], v[24:25]
	v_pk_mul_f32 v[8:9], v[8:9], v[194:195]
	v_mov_b32_dpp v28, v20 row_shl:15 row_mask:0xf bank_mask:0xf bound_ctrl:1
	v_mov_b32_dpp v20, v20 row_shl:14 row_mask:0xf bank_mask:0xf bound_ctrl:1
	v_mov_b32_dpp v48, v16 row_shl:15 row_mask:0xf bank_mask:0xf bound_ctrl:1
	v_mov_b32_dpp v44, v16 row_shl:14 row_mask:0xf bank_mask:0xf bound_ctrl:1
	v_mov_b32_dpp v29, v21 row_shl:15 row_mask:0xf bank_mask:0xf bound_ctrl:1
	v_mov_b32_dpp v21, v21 row_shl:14 row_mask:0xf bank_mask:0xf bound_ctrl:1
	v_mov_b32_dpp v49, v17 row_shl:15 row_mask:0xf bank_mask:0xf bound_ctrl:1
	v_mov_b32_dpp v45, v17 row_shl:14 row_mask:0xf bank_mask:0xf bound_ctrl:1
	v_mov_b32_dpp v32, v22 row_shl:15 row_mask:0xf bank_mask:0xf bound_ctrl:1
	v_mov_b32_dpp v22, v22 row_shl:14 row_mask:0xf bank_mask:0xf bound_ctrl:1
	v_mov_b32_dpp v54, v18 row_shl:15 row_mask:0xf bank_mask:0xf bound_ctrl:1
	v_mov_b32_dpp v18, v18 row_shl:14 row_mask:0xf bank_mask:0xf bound_ctrl:1
	v_mov_b32_dpp v33, v23 row_shl:15 row_mask:0xf bank_mask:0xf bound_ctrl:1
	v_mov_b32_dpp v23, v23 row_shl:14 row_mask:0xf bank_mask:0xf bound_ctrl:1
	v_mov_b32_dpp v55, v19 row_shl:15 row_mask:0xf bank_mask:0xf bound_ctrl:1
	v_mov_b32_dpp v19, v19 row_shl:14 row_mask:0xf bank_mask:0xf bound_ctrl:1
	v_add_f32_dpp v26, v12, v28 row_shr:1 row_mask:0xf bank_mask:0xf bound_ctrl:1
	v_add_f32_dpp v20, v12, v20 row_shr:2 row_mask:0xf bank_mask:0xf bound_ctrl:1
	v_add_f32_dpp v46, v8, v48 row_shr:1 row_mask:0xf bank_mask:0xf bound_ctrl:1
	v_add_f32_dpp v34, v8, v44 row_shr:2 row_mask:0xf bank_mask:0xf bound_ctrl:1
	v_add_f32_dpp v27, v13, v29 row_shr:1 row_mask:0xf bank_mask:0xf bound_ctrl:1
	v_add_f32_dpp v21, v13, v21 row_shr:2 row_mask:0xf bank_mask:0xf bound_ctrl:1
	v_add_f32_dpp v47, v9, v49 row_shr:1 row_mask:0xf bank_mask:0xf bound_ctrl:1
	v_add_f32_dpp v35, v9, v45 row_shr:2 row_mask:0xf bank_mask:0xf bound_ctrl:1
	v_add_f32_dpp v30, v14, v32 row_shr:1 row_mask:0xf bank_mask:0xf bound_ctrl:1
	v_add_f32_dpp v16, v14, v22 row_shr:2 row_mask:0xf bank_mask:0xf bound_ctrl:1
	v_add_f32_dpp v52, v10, v54 row_shr:1 row_mask:0xf bank_mask:0xf bound_ctrl:1
	v_add_f32_dpp v18, v10, v18 row_shr:2 row_mask:0xf bank_mask:0xf bound_ctrl:1
	v_add_f32_dpp v31, v15, v33 row_shr:1 row_mask:0xf bank_mask:0xf bound_ctrl:1
	v_add_f32_dpp v17, v15, v23 row_shr:2 row_mask:0xf bank_mask:0xf bound_ctrl:1
	v_add_f32_dpp v53, v11, v55 row_shr:1 row_mask:0xf bank_mask:0xf bound_ctrl:1
	v_add_f32_dpp v19, v11, v19 row_shr:2 row_mask:0xf bank_mask:0xf bound_ctrl:1
	s_and_saveexec_b64 s[0:1], s[18:19]
	s_cbranch_execz .LBB0_2312
	v_pk_fma_f32 v[16:17], v[78:79], v[16:17], v[82:83]
	v_pk_fma_f32 v[16:17], v[66:67], v[30:31], v[16:17]
	v_pk_fma_f32 v[20:21], v[76:77], v[20:21], v[80:81]
	v_pk_fma_f32 v[16:17], v[14:15], v[62:63], v[16:17]
	v_pk_fma_f32 v[20:21], v[64:65], v[26:27], v[20:21]
	v_mul_f32_e32 v24, 0xbfb8aa3b, v16
	v_mul_f32_e32 v25, 0xbfb8aa3b, v17
	v_pk_fma_f32 v[20:21], v[12:13], v[60:61], v[20:21]
	v_exp_f32_e32 v24, v24
	v_exp_f32_e32 v25, v25
	v_mul_f32_e32 v22, 0xbfb8aa3b, v20
	v_mul_f32_e32 v23, 0xbfb8aa3b, v21
	v_exp_f32_e32 v22, v22
	v_exp_f32_e32 v23, v23
	v_add_f32_e32 v24, 1.0, v24
	v_add_f32_e32 v25, 1.0, v25
	v_rcp_f32_e32 v24, v24
	v_rcp_f32_e32 v25, v25
	v_add_f32_e32 v22, 1.0, v22
	v_add_f32_e32 v23, 1.0, v23
	v_pk_fma_f32 v[18:19], v[90:91], v[18:19], v[94:95]
	v_rcp_f32_e32 v22, v22
	v_rcp_f32_e32 v23, v23
	v_pk_fma_f32 v[18:19], v[86:87], v[52:53], v[18:19]
	v_pk_fma_f32 v[34:35], v[88:89], v[34:35], v[92:93]
	v_pk_fma_f32 v[18:19], v[10:11], v[58:59], v[18:19]
	v_pk_mul_f32 v[16:17], v[16:17], v[24:25]
	v_pk_fma_f32 v[34:35], v[84:85], v[46:47], v[34:35]
	v_pk_mul_f32 v[16:17], v[18:19], v[16:17]
	v_pk_fma_f32 v[26:27], v[8:9], v[56:57], v[34:35]
	v_pk_mul_f32 v[20:21], v[20:21], v[22:23]
	v_cvt_pk_bf16_f32 v19, v16, v17
	v_mov_b64_e32 v[16:17], s[36:37]
	v_pk_mul_f32 v[20:21], v[26:27], v[20:21]
	v_mad_i64_i32 v[16:17], s[12:13], v152, s96, v[16:17]
	v_cvt_pk_bf16_f32 v18, v20, v21
	v_lshl_add_u64 v[16:17], v[190:191], 1, v[16:17]
	global_store_dwordx2 v[16:17], v[18:19], off offset:8
.LBB0_2312:
	s_or_b64 exec, exec, s[0:1]
	v_mov_b32_e32 v193, v192
	v_mov_b32_e32 v16, v192
	v_mov_b32_e32 v17, v192
	v_pk_mul_f32 v[6:7], v[6:7], v[16:17]
	v_pk_mul_f32 v[4:5], v[4:5], v[192:193]
	v_pk_mul_f32 v[2:3], v[2:3], v[16:17]
	v_pk_mul_f32 v[0:1], v[0:1], v[192:193]
	v_mov_b32_dpp v20, v12 row_shl:15 row_mask:0xf bank_mask:0xf bound_ctrl:1
	v_mov_b32_dpp v12, v12 row_shl:14 row_mask:0xf bank_mask:0xf bound_ctrl:1
	v_mov_b32_dpp v32, v8 row_shl:15 row_mask:0xf bank_mask:0xf bound_ctrl:1
	v_mov_b32_dpp v28, v8 row_shl:14 row_mask:0xf bank_mask:0xf bound_ctrl:1
	v_mov_b32_dpp v21, v13 row_shl:15 row_mask:0xf bank_mask:0xf bound_ctrl:1
	v_mov_b32_dpp v13, v13 row_shl:14 row_mask:0xf bank_mask:0xf bound_ctrl:1
	v_mov_b32_dpp v33, v9 row_shl:15 row_mask:0xf bank_mask:0xf bound_ctrl:1
	v_mov_b32_dpp v29, v9 row_shl:14 row_mask:0xf bank_mask:0xf bound_ctrl:1
	v_mov_b32_dpp v24, v14 row_shl:15 row_mask:0xf bank_mask:0xf bound_ctrl:1
	v_mov_b32_dpp v14, v14 row_shl:14 row_mask:0xf bank_mask:0xf bound_ctrl:1
	v_mov_b32_dpp v46, v10 row_shl:15 row_mask:0xf bank_mask:0xf bound_ctrl:1
	v_mov_b32_dpp v10, v10 row_shl:14 row_mask:0xf bank_mask:0xf bound_ctrl:1
	v_mov_b32_dpp v25, v15 row_shl:15 row_mask:0xf bank_mask:0xf bound_ctrl:1
	v_mov_b32_dpp v15, v15 row_shl:14 row_mask:0xf bank_mask:0xf bound_ctrl:1
	v_mov_b32_dpp v47, v11 row_shl:15 row_mask:0xf bank_mask:0xf bound_ctrl:1
	v_mov_b32_dpp v11, v11 row_shl:14 row_mask:0xf bank_mask:0xf bound_ctrl:1
	v_add_f32_dpp v18, v4, v20 row_shr:1 row_mask:0xf bank_mask:0xf bound_ctrl:1
	v_add_f32_dpp v12, v4, v12 row_shr:2 row_mask:0xf bank_mask:0xf bound_ctrl:1
	v_add_f32_dpp v30, v0, v32 row_shr:1 row_mask:0xf bank_mask:0xf bound_ctrl:1
	v_add_f32_dpp v26, v0, v28 row_shr:2 row_mask:0xf bank_mask:0xf bound_ctrl:1
	v_add_f32_dpp v19, v5, v21 row_shr:1 row_mask:0xf bank_mask:0xf bound_ctrl:1
	v_add_f32_dpp v13, v5, v13 row_shr:2 row_mask:0xf bank_mask:0xf bound_ctrl:1
	v_add_f32_dpp v31, v1, v33 row_shr:1 row_mask:0xf bank_mask:0xf bound_ctrl:1
	v_add_f32_dpp v27, v1, v29 row_shr:2 row_mask:0xf bank_mask:0xf bound_ctrl:1
	v_add_f32_dpp v22, v6, v24 row_shr:1 row_mask:0xf bank_mask:0xf bound_ctrl:1
	v_add_f32_dpp v8, v6, v14 row_shr:2 row_mask:0xf bank_mask:0xf bound_ctrl:1
	v_add_f32_dpp v44, v2, v46 row_shr:1 row_mask:0xf bank_mask:0xf bound_ctrl:1
	v_add_f32_dpp v10, v2, v10 row_shr:2 row_mask:0xf bank_mask:0xf bound_ctrl:1
	v_add_f32_dpp v23, v7, v25 row_shr:1 row_mask:0xf bank_mask:0xf bound_ctrl:1
	v_add_f32_dpp v9, v7, v15 row_shr:2 row_mask:0xf bank_mask:0xf bound_ctrl:1
	v_add_f32_dpp v45, v3, v47 row_shr:1 row_mask:0xf bank_mask:0xf bound_ctrl:1
	v_add_f32_dpp v11, v3, v11 row_shr:2 row_mask:0xf bank_mask:0xf bound_ctrl:1
	s_and_saveexec_b64 s[0:1], s[16:17]
	s_cbranch_execz .LBB0_2314
	v_pk_fma_f32 v[8:9], v[78:79], v[8:9], v[82:83]
	v_pk_fma_f32 v[8:9], v[66:67], v[22:23], v[8:9]
	v_pk_fma_f32 v[12:13], v[76:77], v[12:13], v[80:81]
	v_pk_fma_f32 v[8:9], v[6:7], v[62:63], v[8:9]
	v_pk_fma_f32 v[12:13], v[64:65], v[18:19], v[12:13]
	v_mul_f32_e32 v16, 0xbfb8aa3b, v8
	v_mul_f32_e32 v17, 0xbfb8aa3b, v9
	v_pk_fma_f32 v[12:13], v[4:5], v[60:61], v[12:13]
	v_exp_f32_e32 v16, v16
	v_exp_f32_e32 v17, v17
	v_mul_f32_e32 v14, 0xbfb8aa3b, v12
	v_mul_f32_e32 v15, 0xbfb8aa3b, v13
	v_exp_f32_e32 v14, v14
	v_exp_f32_e32 v15, v15
	v_add_f32_e32 v16, 1.0, v16
	v_add_f32_e32 v17, 1.0, v17
	v_rcp_f32_e32 v16, v16
	v_rcp_f32_e32 v17, v17
	v_add_f32_e32 v14, 1.0, v14
	v_add_f32_e32 v15, 1.0, v15
	v_pk_fma_f32 v[10:11], v[90:91], v[10:11], v[94:95]
	v_rcp_f32_e32 v14, v14
	v_rcp_f32_e32 v15, v15
	v_pk_fma_f32 v[10:11], v[86:87], v[44:45], v[10:11]
	v_pk_fma_f32 v[26:27], v[88:89], v[26:27], v[92:93]
	v_pk_fma_f32 v[10:11], v[2:3], v[58:59], v[10:11]
	v_pk_mul_f32 v[8:9], v[8:9], v[16:17]
	v_pk_fma_f32 v[26:27], v[84:85], v[30:31], v[26:27]
	v_pk_mul_f32 v[8:9], v[10:11], v[8:9]
	v_pk_fma_f32 v[18:19], v[0:1], v[56:57], v[26:27]
	v_pk_mul_f32 v[12:13], v[12:13], v[14:15]
	v_cvt_pk_bf16_f32 v11, v8, v9
	v_mov_b64_e32 v[8:9], s[36:37]
	v_pk_mul_f32 v[12:13], v[18:19], v[12:13]
	v_mad_i64_i32 v[8:9], s[12:13], v144, s96, v[8:9]
	v_cvt_pk_bf16_f32 v10, v12, v13
	v_lshl_add_u64 v[8:9], v[190:191], 1, v[8:9]
	global_store_dwordx2 v[8:9], v[10:11], off offset:8
.LBB0_2314:
	s_or_b64 exec, exec, s[0:1]
	v_mov_b32_dpp v12, v4 row_shl:15 row_mask:0xf bank_mask:0xf bound_ctrl:1
	v_mov_b32_dpp v4, v4 row_shl:14 row_mask:0xf bank_mask:0xf bound_ctrl:1
	v_mov_b32_dpp v24, v0 row_shl:15 row_mask:0xf bank_mask:0xf bound_ctrl:1
	v_mov_b32_dpp v20, v0 row_shl:14 row_mask:0xf bank_mask:0xf bound_ctrl:1
	v_mov_b32_dpp v13, v5 row_shl:15 row_mask:0xf bank_mask:0xf bound_ctrl:1
	v_mov_b32_dpp v5, v5 row_shl:14 row_mask:0xf bank_mask:0xf bound_ctrl:1
	v_mov_b32_dpp v25, v1 row_shl:15 row_mask:0xf bank_mask:0xf bound_ctrl:1
	v_mov_b32_dpp v21, v1 row_shl:14 row_mask:0xf bank_mask:0xf bound_ctrl:1
	v_mov_b32_dpp v16, v6 row_shl:15 row_mask:0xf bank_mask:0xf bound_ctrl:1
	v_mov_b32_dpp v6, v6 row_shl:14 row_mask:0xf bank_mask:0xf bound_ctrl:1
	v_mov_b32_dpp v30, v2 row_shl:15 row_mask:0xf bank_mask:0xf bound_ctrl:1
	v_mov_b32_dpp v2, v2 row_shl:14 row_mask:0xf bank_mask:0xf bound_ctrl:1
	v_mov_b32_dpp v17, v7 row_shl:15 row_mask:0xf bank_mask:0xf bound_ctrl:1
	v_mov_b32_dpp v7, v7 row_shl:14 row_mask:0xf bank_mask:0xf bound_ctrl:1
	v_mov_b32_dpp v31, v3 row_shl:15 row_mask:0xf bank_mask:0xf bound_ctrl:1
	v_mov_b32_dpp v3, v3 row_shl:14 row_mask:0xf bank_mask:0xf bound_ctrl:1
	v_add_f32_dpp v10, v40, v12 row_shr:1 row_mask:0xf bank_mask:0xf bound_ctrl:1
	v_add_f32_dpp v4, v40, v4 row_shr:2 row_mask:0xf bank_mask:0xf bound_ctrl:1
	v_add_f32_dpp v22, v36, v24 row_shr:1 row_mask:0xf bank_mask:0xf bound_ctrl:1
	v_add_f32_dpp v18, v36, v20 row_shr:2 row_mask:0xf bank_mask:0xf bound_ctrl:1
	v_add_f32_dpp v11, v41, v13 row_shr:1 row_mask:0xf bank_mask:0xf bound_ctrl:1
	v_add_f32_dpp v5, v41, v5 row_shr:2 row_mask:0xf bank_mask:0xf bound_ctrl:1
	v_add_f32_dpp v23, v37, v25 row_shr:1 row_mask:0xf bank_mask:0xf bound_ctrl:1
	v_add_f32_dpp v19, v37, v21 row_shr:2 row_mask:0xf bank_mask:0xf bound_ctrl:1
	v_add_f32_dpp v14, v42, v16 row_shr:1 row_mask:0xf bank_mask:0xf bound_ctrl:1
	v_add_f32_dpp v0, v42, v6 row_shr:2 row_mask:0xf bank_mask:0xf bound_ctrl:1
	v_add_f32_dpp v28, v38, v30 row_shr:1 row_mask:0xf bank_mask:0xf bound_ctrl:1
	v_add_f32_dpp v2, v38, v2 row_shr:2 row_mask:0xf bank_mask:0xf bound_ctrl:1
	v_add_f32_dpp v15, v43, v17 row_shr:1 row_mask:0xf bank_mask:0xf bound_ctrl:1
	v_add_f32_dpp v1, v43, v7 row_shr:2 row_mask:0xf bank_mask:0xf bound_ctrl:1
	v_add_f32_dpp v29, v39, v31 row_shr:1 row_mask:0xf bank_mask:0xf bound_ctrl:1
	v_add_f32_dpp v3, v39, v3 row_shr:2 row_mask:0xf bank_mask:0xf bound_ctrl:1
	s_and_saveexec_b64 s[0:1], s[26:27]
	s_cbranch_execz .LBB0_2316
	v_pk_fma_f32 v[0:1], v[78:79], v[0:1], v[82:83]
	v_pk_fma_f32 v[0:1], v[66:67], v[14:15], v[0:1]
	v_pk_fma_f32 v[4:5], v[76:77], v[4:5], v[80:81]
	v_pk_fma_f32 v[0:1], v[42:43], v[62:63], v[0:1]
	v_pk_fma_f32 v[4:5], v[64:65], v[10:11], v[4:5]
	v_mul_f32_e32 v8, 0xbfb8aa3b, v0
	v_mul_f32_e32 v9, 0xbfb8aa3b, v1
	v_pk_fma_f32 v[4:5], v[40:41], v[60:61], v[4:5]
	v_exp_f32_e32 v8, v8
	v_exp_f32_e32 v9, v9
	v_mul_f32_e32 v6, 0xbfb8aa3b, v4
	v_mul_f32_e32 v7, 0xbfb8aa3b, v5
	v_exp_f32_e32 v6, v6
	v_exp_f32_e32 v7, v7
	v_add_f32_e32 v8, 1.0, v8
	v_add_f32_e32 v9, 1.0, v9
	v_rcp_f32_e32 v8, v8
	v_rcp_f32_e32 v9, v9
	v_add_f32_e32 v6, 1.0, v6
	v_add_f32_e32 v7, 1.0, v7
	v_pk_fma_f32 v[2:3], v[90:91], v[2:3], v[94:95]
	v_rcp_f32_e32 v6, v6
	v_rcp_f32_e32 v7, v7
	v_pk_fma_f32 v[2:3], v[86:87], v[28:29], v[2:3]
	v_pk_fma_f32 v[18:19], v[88:89], v[18:19], v[92:93]
	v_pk_fma_f32 v[2:3], v[38:39], v[58:59], v[2:3]
	v_pk_mul_f32 v[0:1], v[0:1], v[8:9]
	v_pk_fma_f32 v[18:19], v[84:85], v[22:23], v[18:19]
	v_pk_mul_f32 v[0:1], v[2:3], v[0:1]
	v_pk_fma_f32 v[10:11], v[36:37], v[56:57], v[18:19]
	v_pk_mul_f32 v[4:5], v[4:5], v[6:7]
	v_cvt_pk_bf16_f32 v3, v0, v1
	v_mov_b64_e32 v[0:1], s[36:37]
	v_pk_mul_f32 v[4:5], v[10:11], v[4:5]
	v_mad_i64_i32 v[0:1], s[12:13], v145, s96, v[0:1]
	v_cvt_pk_bf16_f32 v2, v4, v5
	v_lshl_add_u64 v[0:1], v[190:191], 1, v[0:1]
	global_store_dwordx2 v[0:1], v[2:3], off offset:8
